# deterministic adaLN accumulation (2 commutative atomics per element via LDS combine) + EpiRes epilogues (3 sites) with loads issued up front
# speedup vs baseline: 1.0140x; 1.0021x over previous
.LBB0_7:
	s_or_b64 exec, exec, s[54:55]
	s_waitcnt lgkmcnt(0)
	s_barrier
	v_readfirstlane_b32 s88, v192
	s_nop 0
	s_lshr_b32 s88, s88, 8
	s_cmp_lg_u32 s88, 0
	s_cbranch_scc1 .Lada_comb_skip
	v_lshlrev_b32_e32 v162, 2, v145
	v_add_u32_e32 v162, 0x1c000, v162
	ds_read_b32 v163, v162
	ds_read_b32 v164, v162 offset:2560
	ds_read_b32 v165, v162 offset:1024
	ds_read_b32 v166, v162 offset:3584
	ds_read_b32 v167, v162 offset:2048
	ds_read_b32 v168, v162 offset:4608
	v_lshrrev_b32_e32 v169, 7, v145
	v_add_u32_e32 v169, s84, v169
	s_waitcnt lgkmcnt(0)
	v_add_f32_e32 v163, v163, v164
	v_add_f32_e32 v165, v165, v166
	v_add_f32_e32 v167, v167, v168
	v_mad_i64_i32 v[170:171], s[90:91], v169, s78, v[2:3]
	global_atomic_add_f32 v[170:171], v163, off
	v_add_u32_e32 v169, 2, v169
	v_mad_i64_i32 v[170:171], s[90:91], v169, s78, v[2:3]
	global_atomic_add_f32 v[170:171], v165, off
	v_add_u32_e32 v169, 2, v169
	v_mad_i64_i32 v[170:171], s[90:91], v169, s78, v[2:3]
	v_cmp_gt_u32_e32 vcc, 0x80, v145
	s_and_saveexec_b64 s[90:91], vcc
	global_atomic_add_f32 v[170:171], v167, off
	s_or_b64 exec, exec, s[90:91]
.Lada_comb_skip:
	s_add_i32 s34, s34, s35
	s_sub_i32 s63, s63, s35
	s_cmpk_gt_i32 s34, 0x2ff
	s_cbranch_scc1 .LBB0_33

.LBB0_28:
	s_or_b64 exec, exec, s[54:55]
	v_and_b32_e32 v22, 0x7c, v50
	v_mul_lo_u32 v24, v51, s80
	v_lshlrev_b32_e32 v22, 2, v22
	v_add3_u32 v22, s62, v24, v22
	s_waitcnt lgkmcnt(0)
	s_barrier
	ds_write_b128 v22, v[18:21]
	ds_write_b128 v22, v[14:17] offset:512
	ds_write_b128 v22, v[10:13] offset:1024
	ds_write_b128 v22, v[6:9] offset:1536
	ds_write_b128 v22, v[2:5] offset:2048
	s_waitcnt lgkmcnt(0)
	s_barrier
	v_cmp_gt_i32_e32 vcc, s81, v1
	s_and_saveexec_b64 s[54:55], vcc
	s_cbranch_execz .LBB0_7
	v_lshrrev_b32_e32 v160, 8, v192
	v_mul_u32_u24_e32 v160, 0xa00, v160
	v_add_u32_e32 v160, 0x1c000, v160
	s_lshl_b64 s[56:57], s[52:53], 2
	s_add_u32 s58, s12, s56
	s_addc_u32 s59, s33, s57
	s_cmp_eq_u32 s83, 0
	s_mul_i32 s53, s84, 0x3000
	s_cselect_b64 s[56:57], -1, 0
	s_add_i32 s53, s53, s52
	v_and_b32_e32 v2, 0x7f, v1
	v_or_b32_e32 v4, s53, v2
	v_ashrrev_i32_e32 v5, 31, v4
	v_lshlrev_b32_e32 v22, 2, v2
	s_mul_i32 s84, s84, 5
	v_lshl_add_u64 v[2:3], s[58:59], 0, v[22:23]
	v_add_u32_e32 v6, s62, v22
	v_lshl_add_u64 v[4:5], v[4:5], 2, s[22:23]
	s_mov_b64 s[52:53], 0
	s_branch .LBB0_31
.LBB0_30:
	v_and_b32_e32 v8, 0x3fffff80, v1
	v_lshl_add_u32 v14, v8, 2, v6
	ds_read2st64_b32 v[8:9], v14 offset1:10
	ds_read2st64_b32 v[10:11], v14 offset0:20 offset1:30
	ds_read2st64_b32 v[12:13], v14 offset0:40 offset1:50
	ds_read2st64_b32 v[14:15], v14 offset0:60 offset1:70
	v_ashrrev_i32_e32 v16, 7, v1
	v_cmp_lt_i32_e32 vcc, s82, v1
	s_or_b64 s[52:53], vcc, s[52:53]
	s_waitcnt vmcnt(0) lgkmcnt(3)
	v_add_f32_e32 v7, v7, v8
	v_add_f32_e32 v7, v7, v9
	s_waitcnt lgkmcnt(2)
	v_add_f32_e32 v7, v7, v10
	v_add_f32_e32 v7, v7, v11
	s_waitcnt lgkmcnt(1)
	v_add_f32_e32 v7, v7, v12
	v_add_f32_e32 v7, v7, v13
	s_waitcnt lgkmcnt(0)
	v_add_f32_e32 v7, v7, v14
	v_add_u32_e32 v8, s84, v16
	v_add_f32_e32 v7, v7, v15
	v_mad_i64_i32 v[8:9], s[58:59], v8, s78, v[2:3]
	v_lshl_add_u32 v161, v1, 2, v160
	ds_write_b32 v161, v7
	v_add_u32_e32 v7, 0x100, v1
	v_mov_b32_e32 v1, v7
	s_andn2_b64 exec, exec, s[52:53]
	s_cbranch_execz .LBB0_7

.LBB0_1030:
	ds_read_b128 v[148:151], v159
	ds_read_b128 v[152:155], v159 offset:1024
	ds_read_b128 v[162:165], v159 offset:2048
	ds_read_b128 v[166:169], v159 offset:3072
	s_add_u32 s20, s48, 0xffe00080
	s_addc_u32 s21, s49, -1
	s_cmpk_eq_i32 s63, 0x7c
	s_cselect_b32 s21, s17, s21
	s_cselect_b32 s20, s59, s20
	s_cselect_b32 s51, s15, s62
	s_cselect_b32 s50, s60, s61
	v_lshl_add_u64 v[190:191], s[48:49], 0, v[136:137]
	s_add_i32 m0, s37, 0xc000
	ds_read_b128 v[170:173], v160
	ds_read_b128 v[174:177], v160 offset:1024
	ds_read_b128 v[178:181], v160 offset:2048
	ds_read_b128 v[182:185], v160 offset:3072
	ds_read_b128 v[186:189], v160 offset:4096
	ds_read_b128 v[196:199], v160 offset:5120
	ds_read_b128 v[200:203], v160 offset:6144
	ds_read_b128 v[204:207], v160 offset:7168
	global_load_lds_dwordx4 v[190:191], off
	v_lshl_add_u64 v[190:191], s[48:49], 0, v[138:139]
	s_add_i32 m0, s37, 0xe000
	s_nop 0
	global_load_lds_dwordx4 v[190:191], off
	s_waitcnt lgkmcnt(8)
	s_barrier
	s_waitcnt lgkmcnt(0)
	s_setprio 1
	s_waitcnt lgkmcnt(0)
	v_mfma_f32_16x16x32_bf16 v[124:127], v[148:151], v[170:173], v[124:127]
	v_mfma_f32_16x16x32_bf16 v[120:123], v[162:165], v[170:173], v[120:123]
	v_mfma_f32_16x16x32_bf16 v[108:111], v[148:151], v[178:181], v[108:111]
	v_mfma_f32_16x16x32_bf16 v[104:107], v[162:165], v[178:181], v[104:107]
	v_mfma_f32_16x16x32_bf16 v[92:95], v[148:151], v[186:189], v[92:95]
	v_mfma_f32_16x16x32_bf16 v[88:91], v[162:165], v[186:189], v[88:91]
	v_mfma_f32_16x16x32_bf16 v[76:79], v[148:151], v[200:203], v[76:79]
	v_mfma_f32_16x16x32_bf16 v[72:75], v[162:165], v[200:203], v[72:75]
	v_mfma_f32_16x16x32_bf16 v[124:127], v[152:155], v[174:177], v[124:127]
	v_mfma_f32_16x16x32_bf16 v[120:123], v[166:169], v[174:177], v[120:123]
	v_mfma_f32_16x16x32_bf16 v[108:111], v[152:155], v[182:185], v[108:111]
	v_mfma_f32_16x16x32_bf16 v[104:107], v[166:169], v[182:185], v[104:107]
	v_mfma_f32_16x16x32_bf16 v[92:95], v[152:155], v[196:199], v[92:95]
	v_mfma_f32_16x16x32_bf16 v[88:91], v[166:169], v[196:199], v[88:91]
	v_mfma_f32_16x16x32_bf16 v[76:79], v[152:155], v[204:207], v[76:79]
	v_mfma_f32_16x16x32_bf16 v[72:75], v[166:169], v[204:207], v[72:75]
	s_setprio 0
	s_barrier
	s_add_i32 s64, s55, s23
	v_lshl_add_u64 v[190:191], s[50:51], 0, v[132:133]
	s_mov_b32 m0, s64
	ds_read_b128 v[208:211], v161
	ds_read_b128 v[212:215], v161 offset:1024
	ds_read_b128 v[216:219], v161 offset:2048
	ds_read_b128 v[220:223], v161 offset:3072
	global_load_lds_dwordx4 v[190:191], off
	v_lshl_add_u64 v[224:225], s[50:51], 0, v[128:129]
	s_add_i32 m0, s64, 0x2000
	s_nop 0
	global_load_lds_dwordx4 v[224:225], off
	s_barrier
	s_waitcnt lgkmcnt(0)
	s_setprio 1
	s_waitcnt lgkmcnt(0)
	v_mfma_f32_16x16x32_bf16 v[116:119], v[208:211], v[170:173], v[116:119]
	v_mfma_f32_16x16x32_bf16 v[112:115], v[216:219], v[170:173], v[112:115]
	v_mfma_f32_16x16x32_bf16 v[100:103], v[208:211], v[178:181], v[100:103]
	v_mfma_f32_16x16x32_bf16 v[96:99], v[216:219], v[178:181], v[96:99]
	v_mfma_f32_16x16x32_bf16 v[84:87], v[208:211], v[186:189], v[84:87]
	v_mfma_f32_16x16x32_bf16 v[80:83], v[216:219], v[186:189], v[80:83]
	v_mfma_f32_16x16x32_bf16 v[68:71], v[208:211], v[200:203], v[68:71]
	v_mfma_f32_16x16x32_bf16 v[64:67], v[216:219], v[200:203], v[64:67]
	v_mfma_f32_16x16x32_bf16 v[116:119], v[212:215], v[174:177], v[116:119]
	v_mfma_f32_16x16x32_bf16 v[112:115], v[220:223], v[174:177], v[112:115]
	v_mfma_f32_16x16x32_bf16 v[100:103], v[212:215], v[182:185], v[100:103]
	v_mfma_f32_16x16x32_bf16 v[96:99], v[220:223], v[182:185], v[96:99]
	v_mfma_f32_16x16x32_bf16 v[84:87], v[212:215], v[196:199], v[84:87]
	v_mfma_f32_16x16x32_bf16 v[80:83], v[220:223], v[196:199], v[80:83]
	v_mfma_f32_16x16x32_bf16 v[68:71], v[212:215], v[204:207], v[68:71]
	v_mfma_f32_16x16x32_bf16 v[64:67], v[220:223], v[204:207], v[64:67]
	s_setprio 0
	s_mov_b32 m0, s37
	v_lshl_add_u64 v[226:227], s[20:21], 0, v[134:135]
	s_barrier
	ds_read_b128 v[170:173], v160 offset:16384
	ds_read_b128 v[174:177], v160 offset:17408
	ds_read_b128 v[178:181], v160 offset:18432
	ds_read_b128 v[182:185], v160 offset:19456
	ds_read_b128 v[186:189], v160 offset:20480
	ds_read_b128 v[196:199], v160 offset:21504
	ds_read_b128 v[200:203], v160 offset:22528
	ds_read_b128 v[204:207], v160 offset:23552
	global_load_lds_dwordx4 v[226:227], off
	v_lshl_add_u64 v[228:229], s[20:21], 0, v[130:131]
	s_mov_b32 m0, s38
	s_nop 0
	global_load_lds_dwordx4 v[228:229], off
	s_barrier
	s_waitcnt lgkmcnt(0)
	s_setprio 1
	s_waitcnt lgkmcnt(0)
	v_mfma_f32_16x16x32_bf16 v[60:63], v[148:151], v[170:173], v[60:63]
	v_mfma_f32_16x16x32_bf16 v[56:59], v[162:165], v[170:173], v[56:59]
	v_mfma_f32_16x16x32_bf16 v[44:47], v[148:151], v[178:181], v[44:47]
	v_mfma_f32_16x16x32_bf16 v[40:43], v[162:165], v[178:181], v[40:43]
	v_mfma_f32_16x16x32_bf16 v[28:31], v[148:151], v[186:189], v[28:31]
	v_mfma_f32_16x16x32_bf16 v[24:27], v[162:165], v[186:189], v[24:27]
	v_mfma_f32_16x16x32_bf16 v[12:15], v[148:151], v[200:203], v[12:15]
	v_mfma_f32_16x16x32_bf16 v[8:11], v[162:165], v[200:203], v[8:11]
	v_mfma_f32_16x16x32_bf16 v[60:63], v[152:155], v[174:177], v[60:63]
	v_mfma_f32_16x16x32_bf16 v[56:59], v[166:169], v[174:177], v[56:59]
	v_mfma_f32_16x16x32_bf16 v[44:47], v[152:155], v[182:185], v[44:47]
	v_mfma_f32_16x16x32_bf16 v[40:43], v[166:169], v[182:185], v[40:43]
	v_mfma_f32_16x16x32_bf16 v[28:31], v[152:155], v[196:199], v[28:31]
	v_mfma_f32_16x16x32_bf16 v[24:27], v[166:169], v[196:199], v[24:27]
	v_mfma_f32_16x16x32_bf16 v[12:15], v[152:155], v[204:207], v[12:15]
	v_mfma_f32_16x16x32_bf16 v[8:11], v[166:169], v[204:207], v[8:11]
	s_setprio 0
	s_barrier
	s_add_u32 s64, s50, 0x200000
	s_addc_u32 s65, s51, 0
	s_add_i32 s66, s57, s23
	v_lshl_add_u64 v[148:149], s[64:65], 0, v[132:133]
	s_mov_b32 m0, s66
	s_nop 0
	global_load_lds_dwordx4 v[148:149], off
	v_lshl_add_u64 v[148:149], s[64:65], 0, v[128:129]
	s_add_i32 m0, s66, 0x2000
	s_nop 0
	global_load_lds_dwordx4 v[148:149], off
	s_waitcnt vmcnt(6)
	s_barrier
	s_setprio 1
	v_mfma_f32_16x16x32_bf16 v[52:55], v[208:211], v[170:173], v[52:55]
	v_mfma_f32_16x16x32_bf16 v[48:51], v[216:219], v[170:173], v[48:51]
	v_mfma_f32_16x16x32_bf16 v[36:39], v[208:211], v[178:181], v[36:39]
	v_mfma_f32_16x16x32_bf16 v[32:35], v[216:219], v[178:181], v[32:35]
	v_mfma_f32_16x16x32_bf16 v[20:23], v[208:211], v[186:189], v[20:23]
	v_mfma_f32_16x16x32_bf16 v[16:19], v[216:219], v[186:189], v[16:19]
	v_mfma_f32_16x16x32_bf16 v[4:7], v[208:211], v[200:203], v[4:7]
	v_mfma_f32_16x16x32_bf16 v[0:3], v[216:219], v[200:203], v[0:3]
	v_mfma_f32_16x16x32_bf16 v[52:55], v[212:215], v[174:177], v[52:55]
	v_mfma_f32_16x16x32_bf16 v[48:51], v[220:223], v[174:177], v[48:51]
	v_mfma_f32_16x16x32_bf16 v[36:39], v[212:215], v[182:185], v[36:39]
	v_mfma_f32_16x16x32_bf16 v[32:35], v[220:223], v[182:185], v[32:35]
	v_mfma_f32_16x16x32_bf16 v[20:23], v[212:215], v[196:199], v[20:23]
	v_mfma_f32_16x16x32_bf16 v[16:19], v[220:223], v[196:199], v[16:19]
	v_mfma_f32_16x16x32_bf16 v[4:7], v[212:215], v[204:207], v[4:7]
	v_mfma_f32_16x16x32_bf16 v[0:3], v[220:223], v[204:207], v[0:3]
	s_setprio 0
	s_add_i32 s64, 0, 0x18000
	v_add_u32_e32 v166, s64, v156
	s_barrier
	ds_read_b128 v[148:151], v166
	ds_read_b128 v[152:155], v166 offset:1024
	ds_read_b128 v[162:165], v166 offset:2048
	ds_read_b128 v[166:169], v166 offset:3072
	s_add_u32 s20, s20, 0x200000
	s_addc_u32 s21, s21, 0
	s_mov_b32 m0, s39
	v_lshl_add_u64 v[208:209], s[20:21], 0, v[134:135]
	ds_read_b128 v[170:173], v160 offset:32768
	ds_read_b128 v[174:177], v160 offset:33792
	ds_read_b128 v[178:181], v160 offset:34816
	ds_read_b128 v[182:185], v160 offset:35840
	ds_read_b128 v[186:189], v160 offset:36864
	ds_read_b128 v[196:199], v160 offset:37888
	ds_read_b128 v[200:203], v160 offset:38912
	ds_read_b128 v[204:207], v160 offset:39936
	global_load_lds_dwordx4 v[208:209], off
	v_lshl_add_u64 v[208:209], s[20:21], 0, v[130:131]
	s_mov_b32 m0, s47
	s_nop 0
	global_load_lds_dwordx4 v[208:209], off
	s_waitcnt lgkmcnt(8)
	s_barrier
	s_waitcnt lgkmcnt(0)
	s_setprio 1
	s_waitcnt lgkmcnt(0)
	v_mfma_f32_16x16x32_bf16 v[124:127], v[148:151], v[170:173], v[124:127]
	v_mfma_f32_16x16x32_bf16 v[120:123], v[162:165], v[170:173], v[120:123]
	v_mfma_f32_16x16x32_bf16 v[108:111], v[148:151], v[178:181], v[108:111]
	v_mfma_f32_16x16x32_bf16 v[104:107], v[162:165], v[178:181], v[104:107]
	v_mfma_f32_16x16x32_bf16 v[92:95], v[148:151], v[186:189], v[92:95]
	v_mfma_f32_16x16x32_bf16 v[88:91], v[162:165], v[186:189], v[88:91]
	v_mfma_f32_16x16x32_bf16 v[76:79], v[148:151], v[200:203], v[76:79]
	v_mfma_f32_16x16x32_bf16 v[72:75], v[162:165], v[200:203], v[72:75]
	v_mfma_f32_16x16x32_bf16 v[124:127], v[152:155], v[174:177], v[124:127]
	v_mfma_f32_16x16x32_bf16 v[120:123], v[166:169], v[174:177], v[120:123]
	v_mfma_f32_16x16x32_bf16 v[108:111], v[152:155], v[182:185], v[108:111]
	v_mfma_f32_16x16x32_bf16 v[104:107], v[166:169], v[182:185], v[104:107]
	v_mfma_f32_16x16x32_bf16 v[92:95], v[152:155], v[196:199], v[92:95]
	v_mfma_f32_16x16x32_bf16 v[88:91], v[166:169], v[196:199], v[88:91]
	v_mfma_f32_16x16x32_bf16 v[76:79], v[152:155], v[204:207], v[76:79]
	v_mfma_f32_16x16x32_bf16 v[72:75], v[166:169], v[204:207], v[72:75]
	s_setprio 0
	s_barrier
	s_add_i32 s65, 0, 0x1c000
	s_add_i32 s20, s64, s23
	v_add_u32_e32 v195, s65, v156
	v_lshl_add_u64 v[190:191], v[190:191], 0, s[10:11]
	s_mov_b32 m0, s20
	ds_read_b128 v[208:211], v195
	ds_read_b128 v[212:215], v195 offset:1024
	ds_read_b128 v[216:219], v195 offset:2048
	ds_read_b128 v[220:223], v195 offset:3072
	global_load_lds_dwordx4 v[190:191], off
	v_lshl_add_u64 v[190:191], v[224:225], 0, s[10:11]
	s_add_i32 m0, s20, 0x2000
	s_nop 0
	global_load_lds_dwordx4 v[190:191], off
	s_barrier
	s_waitcnt lgkmcnt(0)
	s_setprio 1
	s_waitcnt lgkmcnt(0)
	v_mfma_f32_16x16x32_bf16 v[116:119], v[208:211], v[170:173], v[116:119]
	v_mfma_f32_16x16x32_bf16 v[112:115], v[216:219], v[170:173], v[112:115]
	v_mfma_f32_16x16x32_bf16 v[100:103], v[208:211], v[178:181], v[100:103]
	v_mfma_f32_16x16x32_bf16 v[96:99], v[216:219], v[178:181], v[96:99]
	v_mfma_f32_16x16x32_bf16 v[84:87], v[208:211], v[186:189], v[84:87]
	v_mfma_f32_16x16x32_bf16 v[80:83], v[216:219], v[186:189], v[80:83]
	v_mfma_f32_16x16x32_bf16 v[68:71], v[208:211], v[200:203], v[68:71]
	v_mfma_f32_16x16x32_bf16 v[64:67], v[216:219], v[200:203], v[64:67]
	v_mfma_f32_16x16x32_bf16 v[116:119], v[212:215], v[174:177], v[116:119]
	v_mfma_f32_16x16x32_bf16 v[112:115], v[220:223], v[174:177], v[112:115]
	v_mfma_f32_16x16x32_bf16 v[100:103], v[212:215], v[182:185], v[100:103]
	v_mfma_f32_16x16x32_bf16 v[96:99], v[220:223], v[182:185], v[96:99]
	v_mfma_f32_16x16x32_bf16 v[84:87], v[212:215], v[196:199], v[84:87]
	v_mfma_f32_16x16x32_bf16 v[80:83], v[220:223], v[196:199], v[80:83]
	v_mfma_f32_16x16x32_bf16 v[68:71], v[212:215], v[204:207], v[68:71]
	v_mfma_f32_16x16x32_bf16 v[64:67], v[220:223], v[204:207], v[64:67]
	s_setprio 0
	s_mov_b32 m0, s34
	v_lshl_add_u64 v[190:191], v[226:227], 0, s[10:11]
	s_barrier
	ds_read_b128 v[170:173], v160 offset:49152
	ds_read_b128 v[174:177], v160 offset:50176
	ds_read_b128 v[178:181], v160 offset:51200
	ds_read_b128 v[182:185], v160 offset:52224
	ds_read_b128 v[186:189], v160 offset:53248
	ds_read_b128 v[196:199], v160 offset:54272
	ds_read_b128 v[200:203], v160 offset:55296
	ds_read_b128 v[204:207], v160 offset:56320
	global_load_lds_dwordx4 v[190:191], off
	v_lshl_add_u64 v[190:191], v[228:229], 0, s[10:11]
	s_mov_b32 m0, s35
	s_nop 0
	global_load_lds_dwordx4 v[190:191], off
	s_barrier
	s_waitcnt lgkmcnt(0)
	s_setprio 1
	s_waitcnt lgkmcnt(0)
	v_mfma_f32_16x16x32_bf16 v[60:63], v[148:151], v[170:173], v[60:63]
	v_mfma_f32_16x16x32_bf16 v[56:59], v[162:165], v[170:173], v[56:59]
	v_mfma_f32_16x16x32_bf16 v[44:47], v[148:151], v[178:181], v[44:47]
	v_mfma_f32_16x16x32_bf16 v[40:43], v[162:165], v[178:181], v[40:43]
	v_mfma_f32_16x16x32_bf16 v[28:31], v[148:151], v[186:189], v[28:31]
	v_mfma_f32_16x16x32_bf16 v[24:27], v[162:165], v[186:189], v[24:27]
	v_mfma_f32_16x16x32_bf16 v[12:15], v[148:151], v[200:203], v[12:15]
	v_mfma_f32_16x16x32_bf16 v[8:11], v[162:165], v[200:203], v[8:11]
	v_mfma_f32_16x16x32_bf16 v[60:63], v[152:155], v[174:177], v[60:63]
	v_mfma_f32_16x16x32_bf16 v[56:59], v[166:169], v[174:177], v[56:59]
	v_mfma_f32_16x16x32_bf16 v[44:47], v[152:155], v[182:185], v[44:47]
	v_mfma_f32_16x16x32_bf16 v[40:43], v[166:169], v[182:185], v[40:43]
	v_mfma_f32_16x16x32_bf16 v[28:31], v[152:155], v[196:199], v[28:31]
	v_mfma_f32_16x16x32_bf16 v[24:27], v[166:169], v[196:199], v[24:27]
	v_mfma_f32_16x16x32_bf16 v[12:15], v[152:155], v[204:207], v[12:15]
	v_mfma_f32_16x16x32_bf16 v[8:11], v[166:169], v[204:207], v[8:11]
	s_setprio 0
	s_barrier
	s_add_u32 s20, s50, 0x200080
	s_addc_u32 s21, s51, 0
	s_add_i32 s50, s65, s23
	v_lshl_add_u64 v[148:149], s[20:21], 0, v[132:133]
	s_mov_b32 m0, s50
	s_nop 0
	global_load_lds_dwordx4 v[148:149], off
	v_lshl_add_u64 v[148:149], s[20:21], 0, v[128:129]
	s_add_i32 m0, s50, 0x2000
	s_nop 0
	global_load_lds_dwordx4 v[148:149], off
	s_waitcnt vmcnt(6)
	s_barrier
	s_setprio 1
	v_mfma_f32_16x16x32_bf16 v[52:55], v[208:211], v[170:173], v[52:55]
	v_mfma_f32_16x16x32_bf16 v[48:51], v[216:219], v[170:173], v[48:51]
	v_mfma_f32_16x16x32_bf16 v[36:39], v[208:211], v[178:181], v[36:39]
	v_mfma_f32_16x16x32_bf16 v[32:35], v[216:219], v[178:181], v[32:35]
	v_mfma_f32_16x16x32_bf16 v[20:23], v[208:211], v[186:189], v[20:23]
	v_mfma_f32_16x16x32_bf16 v[16:19], v[216:219], v[186:189], v[16:19]
	v_mfma_f32_16x16x32_bf16 v[4:7], v[208:211], v[200:203], v[4:7]
	v_mfma_f32_16x16x32_bf16 v[0:3], v[216:219], v[200:203], v[0:3]
	v_mfma_f32_16x16x32_bf16 v[52:55], v[212:215], v[174:177], v[52:55]
	v_mfma_f32_16x16x32_bf16 v[48:51], v[220:223], v[174:177], v[48:51]
	v_mfma_f32_16x16x32_bf16 v[36:39], v[212:215], v[182:185], v[36:39]
	v_mfma_f32_16x16x32_bf16 v[32:35], v[220:223], v[182:185], v[32:35]
	v_mfma_f32_16x16x32_bf16 v[20:23], v[212:215], v[196:199], v[20:23]
	v_mfma_f32_16x16x32_bf16 v[16:19], v[220:223], v[196:199], v[16:19]
	v_mfma_f32_16x16x32_bf16 v[4:7], v[212:215], v[204:207], v[4:7]
	v_mfma_f32_16x16x32_bf16 v[0:3], v[220:223], v[204:207], v[0:3]
	s_setprio 0
	s_add_i32 s63, s63, 2
	s_add_u32 s48, s48, 0x100
	s_addc_u32 s49, s49, 0
	s_add_u32 s61, s61, 0x100
	s_addc_u32 s62, s62, 0
	s_cmpk_gt_u32 s63, 0x7d
	s_barrier
	s_cbranch_scc0 .LBB0_1030
	s_lshl_b32 s15, s46, 8
	s_add_i32 s15, s15, s53
	v_or_b32_e32 v154, s15, v147
	s_add_i32 s17, s15, 0xffffe000
	v_lshl_or_b32 v150, s33, 8, v158
	s_lshr_b32 s17, s17, 12
	v_lshlrev_b32_e32 v148, 12, v154
	s_add_i32 s17, s17, 1
	s_cmp_gt_i32 s15, s58
	s_cselect_b32 s17, s17, 0
	s_mul_i32 s17, s17, s56
	v_lshl_add_u32 v148, v150, 1, v148
	s_add_u32 s20, s8, s17
	s_addc_u32 s21, s9, 0
	v_lshlrev_b32_e32 v149, 2, v150
	s_nop 0
	global_load_dwordx4 v[196:199], v149, s[20:21]
	global_load_dwordx4 v[200:203], v149, s[20:21] offset:16
	global_load_dwordx4 v[204:207], v149, s[20:21] offset:512
	global_load_dwordx4 v[208:211], v149, s[20:21] offset:528
	global_load_dwordx4 v[212:215], v148, s[74:75]
	global_load_dwordx4 v[216:219], v148, s[74:75] offset:256
	v_add_u32_e32 v151, 0x10000, v148
	global_load_dwordx4 v[220:223], v151, s[74:75]
	global_load_dwordx4 v[224:227], v151, s[74:75] offset:256
	v_add_u32_e32 v151, 0x20000, v148
	global_load_dwordx4 v[164:167], v151, s[74:75]
	global_load_dwordx4 v[168:171], v151, s[74:75] offset:256
	v_add_u32_e32 v151, 0x30000, v148
	global_load_dwordx4 v[172:175], v151, s[74:75]
	global_load_dwordx4 v[176:179], v151, s[74:75] offset:256
	s_mov_b32 s33, s14
	s_mov_b32 s46, s16
	s_mov_b64 s[50:51], s[44:45]
	s_mov_b64 s[48:49], s[18:19]
	s_waitcnt vmcnt(0)
	v_lshlrev_b32_e32 v180, 16, v212
	v_and_b32_e32 v181, 0xffff0000, v212
	v_lshlrev_b32_e32 v182, 16, v213
	v_and_b32_e32 v183, 0xffff0000, v213
	v_lshlrev_b32_e32 v184, 16, v214
	v_and_b32_e32 v185, 0xffff0000, v214
	v_lshlrev_b32_e32 v186, 16, v215
	v_and_b32_e32 v187, 0xffff0000, v215
	v_pk_fma_f32 v[124:125], v[124:125], v[196:197], v[180:181]
	v_pk_fma_f32 v[126:127], v[126:127], v[198:199], v[182:183]
	v_pk_fma_f32 v[120:121], v[120:121], v[200:201], v[184:185]
	v_pk_fma_f32 v[122:123], v[122:123], v[202:203], v[186:187]
	v_cvt_pk_bf16_f32 v123, v122, v123
	v_cvt_pk_bf16_f32 v122, v120, v121
	v_cvt_pk_bf16_f32 v121, v126, v127
	v_cvt_pk_bf16_f32 v120, v124, v125
	global_store_dwordx4 v148, v[120:123], s[74:75]
	v_lshlrev_b32_e32 v180, 16, v216
	v_and_b32_e32 v181, 0xffff0000, v216
	v_lshlrev_b32_e32 v182, 16, v217
	v_and_b32_e32 v183, 0xffff0000, v217
	v_lshlrev_b32_e32 v184, 16, v218
	v_and_b32_e32 v185, 0xffff0000, v218
	v_lshlrev_b32_e32 v186, 16, v219
	v_and_b32_e32 v187, 0xffff0000, v219
	v_pk_fma_f32 v[116:117], v[116:117], v[204:205], v[180:181]
	v_pk_fma_f32 v[118:119], v[118:119], v[206:207], v[182:183]
	v_pk_fma_f32 v[112:113], v[112:113], v[208:209], v[184:185]
	v_pk_fma_f32 v[114:115], v[114:115], v[210:211], v[186:187]
	v_cvt_pk_bf16_f32 v115, v114, v115
	v_cvt_pk_bf16_f32 v114, v112, v113
	v_cvt_pk_bf16_f32 v113, v118, v119
	v_cvt_pk_bf16_f32 v112, v116, v117
	global_store_dwordx4 v148, v[112:115], s[74:75] offset:256
	v_lshlrev_b32_e32 v180, 16, v220
	v_and_b32_e32 v181, 0xffff0000, v220
	v_lshlrev_b32_e32 v182, 16, v221
	v_and_b32_e32 v183, 0xffff0000, v221
	v_lshlrev_b32_e32 v184, 16, v222
	v_and_b32_e32 v185, 0xffff0000, v222
	v_lshlrev_b32_e32 v186, 16, v223
	v_and_b32_e32 v187, 0xffff0000, v223
	v_pk_fma_f32 v[108:109], v[108:109], v[196:197], v[180:181]
	v_pk_fma_f32 v[110:111], v[110:111], v[198:199], v[182:183]
	v_pk_fma_f32 v[104:105], v[104:105], v[200:201], v[184:185]
	v_pk_fma_f32 v[106:107], v[106:107], v[202:203], v[186:187]
	v_cvt_pk_bf16_f32 v107, v106, v107
	v_cvt_pk_bf16_f32 v106, v104, v105
	v_cvt_pk_bf16_f32 v105, v110, v111
	v_cvt_pk_bf16_f32 v104, v108, v109
	v_add_u32_e32 v151, 0x10000, v148
	global_store_dwordx4 v151, v[104:107], s[74:75]
	v_lshlrev_b32_e32 v180, 16, v224
	v_and_b32_e32 v181, 0xffff0000, v224
	v_lshlrev_b32_e32 v182, 16, v225
	v_and_b32_e32 v183, 0xffff0000, v225
	v_lshlrev_b32_e32 v184, 16, v226
	v_and_b32_e32 v185, 0xffff0000, v226
	v_lshlrev_b32_e32 v186, 16, v227
	v_and_b32_e32 v187, 0xffff0000, v227
	v_pk_fma_f32 v[100:101], v[100:101], v[204:205], v[180:181]
	v_pk_fma_f32 v[102:103], v[102:103], v[206:207], v[182:183]
	v_pk_fma_f32 v[96:97], v[96:97], v[208:209], v[184:185]
	v_pk_fma_f32 v[98:99], v[98:99], v[210:211], v[186:187]
	v_cvt_pk_bf16_f32 v99, v98, v99
	v_cvt_pk_bf16_f32 v98, v96, v97
	v_cvt_pk_bf16_f32 v97, v102, v103
	v_cvt_pk_bf16_f32 v96, v100, v101
	v_add_u32_e32 v151, 0x10000, v148
	global_store_dwordx4 v151, v[96:99], s[74:75] offset:256
	v_add_u32_e32 v151, 0x80000, v148
	global_load_dwordx4 v[212:215], v151, s[74:75]
	global_load_dwordx4 v[216:219], v151, s[74:75] offset:256
	v_add_u32_e32 v151, 0x90000, v148
	global_load_dwordx4 v[220:223], v151, s[74:75]
	global_load_dwordx4 v[224:227], v151, s[74:75] offset:256
	v_lshlrev_b32_e32 v180, 16, v164
	v_and_b32_e32 v181, 0xffff0000, v164
	v_lshlrev_b32_e32 v182, 16, v165
	v_and_b32_e32 v183, 0xffff0000, v165
	v_lshlrev_b32_e32 v184, 16, v166
	v_and_b32_e32 v185, 0xffff0000, v166
	v_lshlrev_b32_e32 v186, 16, v167
	v_and_b32_e32 v187, 0xffff0000, v167
	v_pk_fma_f32 v[92:93], v[92:93], v[196:197], v[180:181]
	v_pk_fma_f32 v[94:95], v[94:95], v[198:199], v[182:183]
	v_pk_fma_f32 v[88:89], v[88:89], v[200:201], v[184:185]
	v_pk_fma_f32 v[90:91], v[90:91], v[202:203], v[186:187]
	v_cvt_pk_bf16_f32 v91, v90, v91
	v_cvt_pk_bf16_f32 v90, v88, v89
	v_cvt_pk_bf16_f32 v89, v94, v95
	v_cvt_pk_bf16_f32 v88, v92, v93
	v_add_u32_e32 v151, 0x20000, v148
	global_store_dwordx4 v151, v[88:91], s[74:75]
	v_lshlrev_b32_e32 v180, 16, v168
	v_and_b32_e32 v181, 0xffff0000, v168
	v_lshlrev_b32_e32 v182, 16, v169
	v_and_b32_e32 v183, 0xffff0000, v169
	v_lshlrev_b32_e32 v184, 16, v170
	v_and_b32_e32 v185, 0xffff0000, v170
	v_lshlrev_b32_e32 v186, 16, v171
	v_and_b32_e32 v187, 0xffff0000, v171
	v_pk_fma_f32 v[84:85], v[84:85], v[204:205], v[180:181]
	v_pk_fma_f32 v[86:87], v[86:87], v[206:207], v[182:183]
	v_pk_fma_f32 v[80:81], v[80:81], v[208:209], v[184:185]
	v_pk_fma_f32 v[82:83], v[82:83], v[210:211], v[186:187]
	v_cvt_pk_bf16_f32 v83, v82, v83
	v_cvt_pk_bf16_f32 v82, v80, v81
	v_cvt_pk_bf16_f32 v81, v86, v87
	v_cvt_pk_bf16_f32 v80, v84, v85
	v_add_u32_e32 v151, 0x20000, v148
	global_store_dwordx4 v151, v[80:83], s[74:75] offset:256
	v_lshlrev_b32_e32 v180, 16, v172
	v_and_b32_e32 v181, 0xffff0000, v172
	v_lshlrev_b32_e32 v182, 16, v173
	v_and_b32_e32 v183, 0xffff0000, v173
	v_lshlrev_b32_e32 v184, 16, v174
	v_and_b32_e32 v185, 0xffff0000, v174
	v_lshlrev_b32_e32 v186, 16, v175
	v_and_b32_e32 v187, 0xffff0000, v175
	v_pk_fma_f32 v[76:77], v[76:77], v[196:197], v[180:181]
	v_pk_fma_f32 v[78:79], v[78:79], v[198:199], v[182:183]
	v_pk_fma_f32 v[72:73], v[72:73], v[200:201], v[184:185]
	v_pk_fma_f32 v[74:75], v[74:75], v[202:203], v[186:187]
	v_cvt_pk_bf16_f32 v75, v74, v75
	v_cvt_pk_bf16_f32 v74, v72, v73
	v_cvt_pk_bf16_f32 v73, v78, v79
	v_cvt_pk_bf16_f32 v72, v76, v77
	v_add_u32_e32 v151, 0x30000, v148
	global_store_dwordx4 v151, v[72:75], s[74:75]
	v_lshlrev_b32_e32 v180, 16, v176
	v_and_b32_e32 v181, 0xffff0000, v176
	v_lshlrev_b32_e32 v182, 16, v177
	v_and_b32_e32 v183, 0xffff0000, v177
	v_lshlrev_b32_e32 v184, 16, v178
	v_and_b32_e32 v185, 0xffff0000, v178
	v_lshlrev_b32_e32 v186, 16, v179
	v_and_b32_e32 v187, 0xffff0000, v179
	v_pk_fma_f32 v[68:69], v[68:69], v[204:205], v[180:181]
	v_pk_fma_f32 v[70:71], v[70:71], v[206:207], v[182:183]
	v_pk_fma_f32 v[64:65], v[64:65], v[208:209], v[184:185]
	v_pk_fma_f32 v[66:67], v[66:67], v[210:211], v[186:187]
	v_cvt_pk_bf16_f32 v67, v66, v67
	v_cvt_pk_bf16_f32 v66, v64, v65
	v_cvt_pk_bf16_f32 v65, v70, v71
	v_cvt_pk_bf16_f32 v64, v68, v69
	v_add_u32_e32 v151, 0x30000, v148
	global_store_dwordx4 v151, v[64:67], s[74:75] offset:256
	v_add_u32_e32 v151, 0xa0000, v148
	global_load_dwordx4 v[164:167], v151, s[74:75]
	global_load_dwordx4 v[168:171], v151, s[74:75] offset:256
	v_add_u32_e32 v151, 0xb0000, v148
	global_load_dwordx4 v[172:175], v151, s[74:75]
	global_load_dwordx4 v[176:179], v151, s[74:75] offset:256
	s_waitcnt vmcnt(0)
	v_lshlrev_b32_e32 v180, 16, v212
	v_and_b32_e32 v181, 0xffff0000, v212
	v_lshlrev_b32_e32 v182, 16, v213
	v_and_b32_e32 v183, 0xffff0000, v213
	v_lshlrev_b32_e32 v184, 16, v214
	v_and_b32_e32 v185, 0xffff0000, v214
	v_lshlrev_b32_e32 v186, 16, v215
	v_and_b32_e32 v187, 0xffff0000, v215
	v_pk_fma_f32 v[60:61], v[60:61], v[196:197], v[180:181]
	v_pk_fma_f32 v[62:63], v[62:63], v[198:199], v[182:183]
	v_pk_fma_f32 v[56:57], v[56:57], v[200:201], v[184:185]
	v_pk_fma_f32 v[58:59], v[58:59], v[202:203], v[186:187]
	v_cvt_pk_bf16_f32 v59, v58, v59
	v_cvt_pk_bf16_f32 v58, v56, v57
	v_cvt_pk_bf16_f32 v57, v62, v63
	v_cvt_pk_bf16_f32 v56, v60, v61
	v_add_u32_e32 v151, 0x80000, v148
	global_store_dwordx4 v151, v[56:59], s[74:75]
	v_lshlrev_b32_e32 v180, 16, v216
	v_and_b32_e32 v181, 0xffff0000, v216
	v_lshlrev_b32_e32 v182, 16, v217
	v_and_b32_e32 v183, 0xffff0000, v217
	v_lshlrev_b32_e32 v184, 16, v218
	v_and_b32_e32 v185, 0xffff0000, v218
	v_lshlrev_b32_e32 v186, 16, v219
	v_and_b32_e32 v187, 0xffff0000, v219
	v_pk_fma_f32 v[52:53], v[52:53], v[204:205], v[180:181]
	v_pk_fma_f32 v[54:55], v[54:55], v[206:207], v[182:183]
	v_pk_fma_f32 v[48:49], v[48:49], v[208:209], v[184:185]
	v_pk_fma_f32 v[50:51], v[50:51], v[210:211], v[186:187]
	v_cvt_pk_bf16_f32 v51, v50, v51
	v_cvt_pk_bf16_f32 v50, v48, v49
	v_cvt_pk_bf16_f32 v49, v54, v55
	v_cvt_pk_bf16_f32 v48, v52, v53
	v_add_u32_e32 v151, 0x80000, v148
	global_store_dwordx4 v151, v[48:51], s[74:75] offset:256
	v_lshlrev_b32_e32 v180, 16, v220
	v_and_b32_e32 v181, 0xffff0000, v220
	v_lshlrev_b32_e32 v182, 16, v221
	v_and_b32_e32 v183, 0xffff0000, v221
	v_lshlrev_b32_e32 v184, 16, v222
	v_and_b32_e32 v185, 0xffff0000, v222
	v_lshlrev_b32_e32 v186, 16, v223
	v_and_b32_e32 v187, 0xffff0000, v223
	v_pk_fma_f32 v[44:45], v[44:45], v[196:197], v[180:181]
	v_pk_fma_f32 v[46:47], v[46:47], v[198:199], v[182:183]
	v_pk_fma_f32 v[40:41], v[40:41], v[200:201], v[184:185]
	v_pk_fma_f32 v[42:43], v[42:43], v[202:203], v[186:187]
	v_cvt_pk_bf16_f32 v43, v42, v43
	v_cvt_pk_bf16_f32 v42, v40, v41
	v_cvt_pk_bf16_f32 v41, v46, v47
	v_cvt_pk_bf16_f32 v40, v44, v45
	v_add_u32_e32 v151, 0x90000, v148
	global_store_dwordx4 v151, v[40:43], s[74:75]
	v_lshlrev_b32_e32 v180, 16, v224
	v_and_b32_e32 v181, 0xffff0000, v224
	v_lshlrev_b32_e32 v182, 16, v225
	v_and_b32_e32 v183, 0xffff0000, v225
	v_lshlrev_b32_e32 v184, 16, v226
	v_and_b32_e32 v185, 0xffff0000, v226
	v_lshlrev_b32_e32 v186, 16, v227
	v_and_b32_e32 v187, 0xffff0000, v227
	v_pk_fma_f32 v[36:37], v[36:37], v[204:205], v[180:181]
	v_pk_fma_f32 v[38:39], v[38:39], v[206:207], v[182:183]
	v_pk_fma_f32 v[32:33], v[32:33], v[208:209], v[184:185]
	v_pk_fma_f32 v[34:35], v[34:35], v[210:211], v[186:187]
	v_cvt_pk_bf16_f32 v35, v34, v35
	v_cvt_pk_bf16_f32 v34, v32, v33
	v_cvt_pk_bf16_f32 v33, v38, v39
	v_cvt_pk_bf16_f32 v32, v36, v37
	v_add_u32_e32 v151, 0x90000, v148
	global_store_dwordx4 v151, v[32:35], s[74:75] offset:256
	v_lshlrev_b32_e32 v180, 16, v164
	v_and_b32_e32 v181, 0xffff0000, v164
	v_lshlrev_b32_e32 v182, 16, v165
	v_and_b32_e32 v183, 0xffff0000, v165
	v_lshlrev_b32_e32 v184, 16, v166
	v_and_b32_e32 v185, 0xffff0000, v166
	v_lshlrev_b32_e32 v186, 16, v167
	v_and_b32_e32 v187, 0xffff0000, v167
	v_pk_fma_f32 v[28:29], v[28:29], v[196:197], v[180:181]
	v_pk_fma_f32 v[30:31], v[30:31], v[198:199], v[182:183]
	v_pk_fma_f32 v[24:25], v[24:25], v[200:201], v[184:185]
	v_pk_fma_f32 v[26:27], v[26:27], v[202:203], v[186:187]
	v_cvt_pk_bf16_f32 v27, v26, v27
	v_cvt_pk_bf16_f32 v26, v24, v25
	v_cvt_pk_bf16_f32 v25, v30, v31
	v_cvt_pk_bf16_f32 v24, v28, v29
	v_add_u32_e32 v151, 0xa0000, v148
	global_store_dwordx4 v151, v[24:27], s[74:75]
	v_lshlrev_b32_e32 v180, 16, v168
	v_and_b32_e32 v181, 0xffff0000, v168
	v_lshlrev_b32_e32 v182, 16, v169
	v_and_b32_e32 v183, 0xffff0000, v169
	v_lshlrev_b32_e32 v184, 16, v170
	v_and_b32_e32 v185, 0xffff0000, v170
	v_lshlrev_b32_e32 v186, 16, v171
	v_and_b32_e32 v187, 0xffff0000, v171
	v_pk_fma_f32 v[20:21], v[20:21], v[204:205], v[180:181]
	v_pk_fma_f32 v[22:23], v[22:23], v[206:207], v[182:183]
	v_pk_fma_f32 v[16:17], v[16:17], v[208:209], v[184:185]
	v_pk_fma_f32 v[18:19], v[18:19], v[210:211], v[186:187]
	v_cvt_pk_bf16_f32 v19, v18, v19
	v_cvt_pk_bf16_f32 v18, v16, v17
	v_cvt_pk_bf16_f32 v17, v22, v23
	v_cvt_pk_bf16_f32 v16, v20, v21
	v_add_u32_e32 v151, 0xa0000, v148
	global_store_dwordx4 v151, v[16:19], s[74:75] offset:256
	v_lshlrev_b32_e32 v180, 16, v172
	v_and_b32_e32 v181, 0xffff0000, v172
	v_lshlrev_b32_e32 v182, 16, v173
	v_and_b32_e32 v183, 0xffff0000, v173
	v_lshlrev_b32_e32 v184, 16, v174
	v_and_b32_e32 v185, 0xffff0000, v174
	v_lshlrev_b32_e32 v186, 16, v175
	v_and_b32_e32 v187, 0xffff0000, v175
	v_pk_fma_f32 v[12:13], v[12:13], v[196:197], v[180:181]
	v_pk_fma_f32 v[14:15], v[14:15], v[198:199], v[182:183]
	v_pk_fma_f32 v[8:9], v[8:9], v[200:201], v[184:185]
	v_pk_fma_f32 v[10:11], v[10:11], v[202:203], v[186:187]
	v_cvt_pk_bf16_f32 v11, v10, v11
	v_cvt_pk_bf16_f32 v10, v8, v9
	v_cvt_pk_bf16_f32 v9, v14, v15
	v_cvt_pk_bf16_f32 v8, v12, v13
	v_add_u32_e32 v151, 0xb0000, v148
	global_store_dwordx4 v151, v[8:11], s[74:75]
	v_lshlrev_b32_e32 v180, 16, v176
	v_and_b32_e32 v181, 0xffff0000, v176
	v_lshlrev_b32_e32 v182, 16, v177
	v_and_b32_e32 v183, 0xffff0000, v177
	v_lshlrev_b32_e32 v184, 16, v178
	v_and_b32_e32 v185, 0xffff0000, v178
	v_lshlrev_b32_e32 v186, 16, v179
	v_and_b32_e32 v187, 0xffff0000, v179
	v_pk_fma_f32 v[4:5], v[4:5], v[204:205], v[180:181]
	v_pk_fma_f32 v[6:7], v[6:7], v[206:207], v[182:183]
	v_pk_fma_f32 v[0:1], v[0:1], v[208:209], v[184:185]
	v_pk_fma_f32 v[2:3], v[2:3], v[210:211], v[186:187]
	v_cvt_pk_bf16_f32 v3, v2, v3
	v_cvt_pk_bf16_f32 v2, v0, v1
	v_cvt_pk_bf16_f32 v1, v6, v7
	v_cvt_pk_bf16_f32 v0, v4, v5
	v_add_u32_e32 v151, 0xb0000, v148
	global_store_dwordx4 v151, v[0:3], s[74:75] offset:256
	s_and_b64 vcc, exec, s[0:1]
	s_cbranch_vccz .LBB0_1027
	s_waitcnt vmcnt(0)
	s_cmpk_gt_u32 s12, 0xff
	s_cbranch_scc1 .LBB0_1034
	s_barrier

.LBB0_1346:
	ds_read_b128 v[148:151], v158
	ds_read_b128 v[152:155], v158 offset:1024
	ds_read_b128 v[162:165], v158 offset:2048
	ds_read_b128 v[166:169], v158 offset:3072
	s_add_u32 s20, s38, 0xfff80080
	s_addc_u32 s21, s39, -1
	s_cmp_eq_u32 s61, 28
	s_cselect_b32 s21, s17, s21
	s_cselect_b32 s20, s57, s20
	s_cselect_b32 s45, s15, s60
	s_cselect_b32 s44, s58, s59
	v_lshl_add_u64 v[190:191], s[38:39], 0, v[136:137]
	s_add_i32 m0, s37, 0xc000
	ds_read_b128 v[170:173], v159
	ds_read_b128 v[174:177], v159 offset:1024
	ds_read_b128 v[178:181], v159 offset:2048
	ds_read_b128 v[182:185], v159 offset:3072
	ds_read_b128 v[186:189], v159 offset:4096
	ds_read_b128 v[196:199], v159 offset:5120
	ds_read_b128 v[200:203], v159 offset:6144
	ds_read_b128 v[204:207], v159 offset:7168
	global_load_lds_dwordx4 v[190:191], off
	v_lshl_add_u64 v[190:191], s[38:39], 0, v[138:139]
	s_add_i32 m0, s37, 0xe000
	s_nop 0
	global_load_lds_dwordx4 v[190:191], off
	s_waitcnt lgkmcnt(8)
	s_barrier
	s_waitcnt lgkmcnt(0)
	s_setprio 1
	s_waitcnt lgkmcnt(0)
	v_mfma_f32_16x16x32_bf16 v[124:127], v[148:151], v[170:173], v[124:127]
	v_mfma_f32_16x16x32_bf16 v[120:123], v[162:165], v[170:173], v[120:123]
	v_mfma_f32_16x16x32_bf16 v[108:111], v[148:151], v[178:181], v[108:111]
	v_mfma_f32_16x16x32_bf16 v[104:107], v[162:165], v[178:181], v[104:107]
	v_mfma_f32_16x16x32_bf16 v[92:95], v[148:151], v[186:189], v[92:95]
	v_mfma_f32_16x16x32_bf16 v[88:91], v[162:165], v[186:189], v[88:91]
	v_mfma_f32_16x16x32_bf16 v[76:79], v[148:151], v[200:203], v[76:79]
	v_mfma_f32_16x16x32_bf16 v[72:75], v[162:165], v[200:203], v[72:75]
	v_mfma_f32_16x16x32_bf16 v[124:127], v[152:155], v[174:177], v[124:127]
	v_mfma_f32_16x16x32_bf16 v[120:123], v[166:169], v[174:177], v[120:123]
	v_mfma_f32_16x16x32_bf16 v[108:111], v[152:155], v[182:185], v[108:111]
	v_mfma_f32_16x16x32_bf16 v[104:107], v[166:169], v[182:185], v[104:107]
	v_mfma_f32_16x16x32_bf16 v[92:95], v[152:155], v[196:199], v[92:95]
	v_mfma_f32_16x16x32_bf16 v[88:91], v[166:169], v[196:199], v[88:91]
	v_mfma_f32_16x16x32_bf16 v[76:79], v[152:155], v[204:207], v[76:79]
	v_mfma_f32_16x16x32_bf16 v[72:75], v[166:169], v[204:207], v[72:75]
	s_setprio 0
	s_barrier
	s_add_i32 s62, s53, s23
	v_lshl_add_u64 v[190:191], s[44:45], 0, v[132:133]
	s_mov_b32 m0, s62
	ds_read_b128 v[208:211], v160
	ds_read_b128 v[212:215], v160 offset:1024
	ds_read_b128 v[216:219], v160 offset:2048
	ds_read_b128 v[220:223], v160 offset:3072
	global_load_lds_dwordx4 v[190:191], off
	v_lshl_add_u64 v[224:225], s[44:45], 0, v[128:129]
	s_add_i32 m0, s62, 0x2000
	s_nop 0
	global_load_lds_dwordx4 v[224:225], off
	s_barrier
	s_waitcnt lgkmcnt(0)
	s_setprio 1
	s_waitcnt lgkmcnt(0)
	v_mfma_f32_16x16x32_bf16 v[116:119], v[208:211], v[170:173], v[116:119]
	v_mfma_f32_16x16x32_bf16 v[112:115], v[216:219], v[170:173], v[112:115]
	v_mfma_f32_16x16x32_bf16 v[100:103], v[208:211], v[178:181], v[100:103]
	v_mfma_f32_16x16x32_bf16 v[96:99], v[216:219], v[178:181], v[96:99]
	v_mfma_f32_16x16x32_bf16 v[84:87], v[208:211], v[186:189], v[84:87]
	v_mfma_f32_16x16x32_bf16 v[80:83], v[216:219], v[186:189], v[80:83]
	v_mfma_f32_16x16x32_bf16 v[68:71], v[208:211], v[200:203], v[68:71]
	v_mfma_f32_16x16x32_bf16 v[64:67], v[216:219], v[200:203], v[64:67]
	v_mfma_f32_16x16x32_bf16 v[116:119], v[212:215], v[174:177], v[116:119]
	v_mfma_f32_16x16x32_bf16 v[112:115], v[220:223], v[174:177], v[112:115]
	v_mfma_f32_16x16x32_bf16 v[100:103], v[212:215], v[182:185], v[100:103]
	v_mfma_f32_16x16x32_bf16 v[96:99], v[220:223], v[182:185], v[96:99]
	v_mfma_f32_16x16x32_bf16 v[84:87], v[212:215], v[196:199], v[84:87]
	v_mfma_f32_16x16x32_bf16 v[80:83], v[220:223], v[196:199], v[80:83]
	v_mfma_f32_16x16x32_bf16 v[68:71], v[212:215], v[204:207], v[68:71]
	v_mfma_f32_16x16x32_bf16 v[64:67], v[220:223], v[204:207], v[64:67]
	s_setprio 0
	s_mov_b32 m0, s37
	v_lshl_add_u64 v[226:227], s[20:21], 0, v[134:135]
	s_barrier
	ds_read_b128 v[170:173], v159 offset:16384
	ds_read_b128 v[174:177], v159 offset:17408
	ds_read_b128 v[178:181], v159 offset:18432
	ds_read_b128 v[182:185], v159 offset:19456
	ds_read_b128 v[186:189], v159 offset:20480
	ds_read_b128 v[196:199], v159 offset:21504
	ds_read_b128 v[200:203], v159 offset:22528
	ds_read_b128 v[204:207], v159 offset:23552
	global_load_lds_dwordx4 v[226:227], off
	v_lshl_add_u64 v[228:229], s[20:21], 0, v[130:131]
	s_mov_b32 m0, s47
	s_nop 0
	global_load_lds_dwordx4 v[228:229], off
	s_barrier
	s_waitcnt lgkmcnt(0)
	s_setprio 1
	s_waitcnt lgkmcnt(0)
	v_mfma_f32_16x16x32_bf16 v[60:63], v[148:151], v[170:173], v[60:63]
	v_mfma_f32_16x16x32_bf16 v[56:59], v[162:165], v[170:173], v[56:59]
	v_mfma_f32_16x16x32_bf16 v[44:47], v[148:151], v[178:181], v[44:47]
	v_mfma_f32_16x16x32_bf16 v[40:43], v[162:165], v[178:181], v[40:43]
	v_mfma_f32_16x16x32_bf16 v[28:31], v[148:151], v[186:189], v[28:31]
	v_mfma_f32_16x16x32_bf16 v[24:27], v[162:165], v[186:189], v[24:27]
	v_mfma_f32_16x16x32_bf16 v[12:15], v[148:151], v[200:203], v[12:15]
	v_mfma_f32_16x16x32_bf16 v[8:11], v[162:165], v[200:203], v[8:11]
	v_mfma_f32_16x16x32_bf16 v[60:63], v[152:155], v[174:177], v[60:63]
	v_mfma_f32_16x16x32_bf16 v[56:59], v[166:169], v[174:177], v[56:59]
	v_mfma_f32_16x16x32_bf16 v[44:47], v[152:155], v[182:185], v[44:47]
	v_mfma_f32_16x16x32_bf16 v[40:43], v[166:169], v[182:185], v[40:43]
	v_mfma_f32_16x16x32_bf16 v[28:31], v[152:155], v[196:199], v[28:31]
	v_mfma_f32_16x16x32_bf16 v[24:27], v[166:169], v[196:199], v[24:27]
	v_mfma_f32_16x16x32_bf16 v[12:15], v[152:155], v[204:207], v[12:15]
	v_mfma_f32_16x16x32_bf16 v[8:11], v[166:169], v[204:207], v[8:11]
	s_setprio 0
	s_barrier
	s_add_u32 s62, s44, 0x80000
	s_addc_u32 s63, s45, 0
	s_add_i32 s64, s55, s23
	v_lshl_add_u64 v[148:149], s[62:63], 0, v[132:133]
	s_mov_b32 m0, s64
	s_nop 0
	global_load_lds_dwordx4 v[148:149], off
	v_lshl_add_u64 v[148:149], s[62:63], 0, v[128:129]
	s_add_i32 m0, s64, 0x2000
	s_nop 0
	global_load_lds_dwordx4 v[148:149], off
	s_waitcnt vmcnt(6)
	s_barrier
	s_setprio 1
	v_mfma_f32_16x16x32_bf16 v[52:55], v[208:211], v[170:173], v[52:55]
	v_mfma_f32_16x16x32_bf16 v[48:51], v[216:219], v[170:173], v[48:51]
	v_mfma_f32_16x16x32_bf16 v[36:39], v[208:211], v[178:181], v[36:39]
	v_mfma_f32_16x16x32_bf16 v[32:35], v[216:219], v[178:181], v[32:35]
	v_mfma_f32_16x16x32_bf16 v[20:23], v[208:211], v[186:189], v[20:23]
	v_mfma_f32_16x16x32_bf16 v[16:19], v[216:219], v[186:189], v[16:19]
	v_mfma_f32_16x16x32_bf16 v[4:7], v[208:211], v[200:203], v[4:7]
	v_mfma_f32_16x16x32_bf16 v[0:3], v[216:219], v[200:203], v[0:3]
	v_mfma_f32_16x16x32_bf16 v[52:55], v[212:215], v[174:177], v[52:55]
	v_mfma_f32_16x16x32_bf16 v[48:51], v[220:223], v[174:177], v[48:51]
	v_mfma_f32_16x16x32_bf16 v[36:39], v[212:215], v[182:185], v[36:39]
	v_mfma_f32_16x16x32_bf16 v[32:35], v[220:223], v[182:185], v[32:35]
	v_mfma_f32_16x16x32_bf16 v[20:23], v[212:215], v[196:199], v[20:23]
	v_mfma_f32_16x16x32_bf16 v[16:19], v[220:223], v[196:199], v[16:19]
	v_mfma_f32_16x16x32_bf16 v[4:7], v[212:215], v[204:207], v[4:7]
	v_mfma_f32_16x16x32_bf16 v[0:3], v[220:223], v[204:207], v[0:3]
	s_setprio 0
	s_add_i32 s62, 0, 0x18000
	v_add_u32_e32 v161, s62, v147
	s_barrier
	ds_read_b128 v[148:151], v161
	ds_read_b128 v[152:155], v161 offset:1024
	ds_read_b128 v[162:165], v161 offset:2048
	ds_read_b128 v[166:169], v161 offset:3072
	s_add_u32 s20, s20, 0x80000
	s_addc_u32 s21, s21, 0
	s_mov_b32 m0, s48
	v_lshl_add_u64 v[208:209], s[20:21], 0, v[134:135]
	ds_read_b128 v[170:173], v159 offset:32768
	ds_read_b128 v[174:177], v159 offset:33792
	ds_read_b128 v[178:181], v159 offset:34816
	ds_read_b128 v[182:185], v159 offset:35840
	ds_read_b128 v[186:189], v159 offset:36864
	ds_read_b128 v[196:199], v159 offset:37888
	ds_read_b128 v[200:203], v159 offset:38912
	ds_read_b128 v[204:207], v159 offset:39936
	global_load_lds_dwordx4 v[208:209], off
	v_lshl_add_u64 v[208:209], s[20:21], 0, v[130:131]
	s_mov_b32 m0, s49
	s_nop 0
	global_load_lds_dwordx4 v[208:209], off
	s_waitcnt lgkmcnt(8)
	s_barrier
	s_waitcnt lgkmcnt(0)
	s_setprio 1
	s_waitcnt lgkmcnt(0)
	v_mfma_f32_16x16x32_bf16 v[124:127], v[148:151], v[170:173], v[124:127]
	v_mfma_f32_16x16x32_bf16 v[120:123], v[162:165], v[170:173], v[120:123]
	v_mfma_f32_16x16x32_bf16 v[108:111], v[148:151], v[178:181], v[108:111]
	v_mfma_f32_16x16x32_bf16 v[104:107], v[162:165], v[178:181], v[104:107]
	v_mfma_f32_16x16x32_bf16 v[92:95], v[148:151], v[186:189], v[92:95]
	v_mfma_f32_16x16x32_bf16 v[88:91], v[162:165], v[186:189], v[88:91]
	v_mfma_f32_16x16x32_bf16 v[76:79], v[148:151], v[200:203], v[76:79]
	v_mfma_f32_16x16x32_bf16 v[72:75], v[162:165], v[200:203], v[72:75]
	v_mfma_f32_16x16x32_bf16 v[124:127], v[152:155], v[174:177], v[124:127]
	v_mfma_f32_16x16x32_bf16 v[120:123], v[166:169], v[174:177], v[120:123]
	v_mfma_f32_16x16x32_bf16 v[108:111], v[152:155], v[182:185], v[108:111]
	v_mfma_f32_16x16x32_bf16 v[104:107], v[166:169], v[182:185], v[104:107]
	v_mfma_f32_16x16x32_bf16 v[92:95], v[152:155], v[196:199], v[92:95]
	v_mfma_f32_16x16x32_bf16 v[88:91], v[166:169], v[196:199], v[88:91]
	v_mfma_f32_16x16x32_bf16 v[76:79], v[152:155], v[204:207], v[76:79]
	v_mfma_f32_16x16x32_bf16 v[72:75], v[166:169], v[204:207], v[72:75]
	s_setprio 0
	s_barrier
	s_add_i32 s63, 0, 0x1c000
	s_add_i32 s20, s62, s23
	v_add_u32_e32 v161, s63, v147
	v_lshl_add_u64 v[190:191], v[190:191], 0, s[10:11]
	s_mov_b32 m0, s20
	ds_read_b128 v[208:211], v161
	ds_read_b128 v[212:215], v161 offset:1024
	ds_read_b128 v[216:219], v161 offset:2048
	ds_read_b128 v[220:223], v161 offset:3072
	global_load_lds_dwordx4 v[190:191], off
	v_lshl_add_u64 v[190:191], v[224:225], 0, s[10:11]
	s_add_i32 m0, s20, 0x2000
	s_nop 0
	global_load_lds_dwordx4 v[190:191], off
	s_barrier
	s_waitcnt lgkmcnt(0)
	s_setprio 1
	s_waitcnt lgkmcnt(0)
	v_mfma_f32_16x16x32_bf16 v[116:119], v[208:211], v[170:173], v[116:119]
	v_mfma_f32_16x16x32_bf16 v[112:115], v[216:219], v[170:173], v[112:115]
	v_mfma_f32_16x16x32_bf16 v[100:103], v[208:211], v[178:181], v[100:103]
	v_mfma_f32_16x16x32_bf16 v[96:99], v[216:219], v[178:181], v[96:99]
	v_mfma_f32_16x16x32_bf16 v[84:87], v[208:211], v[186:189], v[84:87]
	v_mfma_f32_16x16x32_bf16 v[80:83], v[216:219], v[186:189], v[80:83]
	v_mfma_f32_16x16x32_bf16 v[68:71], v[208:211], v[200:203], v[68:71]
	v_mfma_f32_16x16x32_bf16 v[64:67], v[216:219], v[200:203], v[64:67]
	v_mfma_f32_16x16x32_bf16 v[116:119], v[212:215], v[174:177], v[116:119]
	v_mfma_f32_16x16x32_bf16 v[112:115], v[220:223], v[174:177], v[112:115]
	v_mfma_f32_16x16x32_bf16 v[100:103], v[212:215], v[182:185], v[100:103]
	v_mfma_f32_16x16x32_bf16 v[96:99], v[220:223], v[182:185], v[96:99]
	v_mfma_f32_16x16x32_bf16 v[84:87], v[212:215], v[196:199], v[84:87]
	v_mfma_f32_16x16x32_bf16 v[80:83], v[220:223], v[196:199], v[80:83]
	v_mfma_f32_16x16x32_bf16 v[68:71], v[212:215], v[204:207], v[68:71]
	v_mfma_f32_16x16x32_bf16 v[64:67], v[220:223], v[204:207], v[64:67]
	s_setprio 0
	s_mov_b32 m0, s34
	v_lshl_add_u64 v[190:191], v[226:227], 0, s[10:11]
	s_barrier
	ds_read_b128 v[170:173], v159 offset:49152
	ds_read_b128 v[174:177], v159 offset:50176
	ds_read_b128 v[178:181], v159 offset:51200
	ds_read_b128 v[182:185], v159 offset:52224
	ds_read_b128 v[186:189], v159 offset:53248
	ds_read_b128 v[196:199], v159 offset:54272
	ds_read_b128 v[200:203], v159 offset:55296
	ds_read_b128 v[204:207], v159 offset:56320
	global_load_lds_dwordx4 v[190:191], off
	v_lshl_add_u64 v[190:191], v[228:229], 0, s[10:11]
	s_mov_b32 m0, s35
	s_nop 0
	global_load_lds_dwordx4 v[190:191], off
	s_barrier
	s_waitcnt lgkmcnt(0)
	s_setprio 1
	s_waitcnt lgkmcnt(0)
	v_mfma_f32_16x16x32_bf16 v[60:63], v[148:151], v[170:173], v[60:63]
	v_mfma_f32_16x16x32_bf16 v[56:59], v[162:165], v[170:173], v[56:59]
	v_mfma_f32_16x16x32_bf16 v[44:47], v[148:151], v[178:181], v[44:47]
	v_mfma_f32_16x16x32_bf16 v[40:43], v[162:165], v[178:181], v[40:43]
	v_mfma_f32_16x16x32_bf16 v[28:31], v[148:151], v[186:189], v[28:31]
	v_mfma_f32_16x16x32_bf16 v[24:27], v[162:165], v[186:189], v[24:27]
	v_mfma_f32_16x16x32_bf16 v[12:15], v[148:151], v[200:203], v[12:15]
	v_mfma_f32_16x16x32_bf16 v[8:11], v[162:165], v[200:203], v[8:11]
	v_mfma_f32_16x16x32_bf16 v[60:63], v[152:155], v[174:177], v[60:63]
	v_mfma_f32_16x16x32_bf16 v[56:59], v[166:169], v[174:177], v[56:59]
	v_mfma_f32_16x16x32_bf16 v[44:47], v[152:155], v[182:185], v[44:47]
	v_mfma_f32_16x16x32_bf16 v[40:43], v[166:169], v[182:185], v[40:43]
	v_mfma_f32_16x16x32_bf16 v[28:31], v[152:155], v[196:199], v[28:31]
	v_mfma_f32_16x16x32_bf16 v[24:27], v[166:169], v[196:199], v[24:27]
	v_mfma_f32_16x16x32_bf16 v[12:15], v[152:155], v[204:207], v[12:15]
	v_mfma_f32_16x16x32_bf16 v[8:11], v[166:169], v[204:207], v[8:11]
	s_setprio 0
	s_barrier
	s_add_u32 s20, s44, 0x80080
	s_addc_u32 s21, s45, 0
	s_add_i32 s44, s63, s23
	v_lshl_add_u64 v[148:149], s[20:21], 0, v[132:133]
	s_mov_b32 m0, s44
	s_nop 0
	global_load_lds_dwordx4 v[148:149], off
	v_lshl_add_u64 v[148:149], s[20:21], 0, v[128:129]
	s_add_i32 m0, s44, 0x2000
	s_nop 0
	global_load_lds_dwordx4 v[148:149], off
	s_waitcnt vmcnt(6)
	s_barrier
	s_setprio 1
	v_mfma_f32_16x16x32_bf16 v[52:55], v[208:211], v[170:173], v[52:55]
	v_mfma_f32_16x16x32_bf16 v[48:51], v[216:219], v[170:173], v[48:51]
	v_mfma_f32_16x16x32_bf16 v[36:39], v[208:211], v[178:181], v[36:39]
	v_mfma_f32_16x16x32_bf16 v[32:35], v[216:219], v[178:181], v[32:35]
	v_mfma_f32_16x16x32_bf16 v[20:23], v[208:211], v[186:189], v[20:23]
	v_mfma_f32_16x16x32_bf16 v[16:19], v[216:219], v[186:189], v[16:19]
	v_mfma_f32_16x16x32_bf16 v[4:7], v[208:211], v[200:203], v[4:7]
	v_mfma_f32_16x16x32_bf16 v[0:3], v[216:219], v[200:203], v[0:3]
	v_mfma_f32_16x16x32_bf16 v[52:55], v[212:215], v[174:177], v[52:55]
	v_mfma_f32_16x16x32_bf16 v[48:51], v[220:223], v[174:177], v[48:51]
	v_mfma_f32_16x16x32_bf16 v[36:39], v[212:215], v[182:185], v[36:39]
	v_mfma_f32_16x16x32_bf16 v[32:35], v[220:223], v[182:185], v[32:35]
	v_mfma_f32_16x16x32_bf16 v[20:23], v[212:215], v[196:199], v[20:23]
	v_mfma_f32_16x16x32_bf16 v[16:19], v[220:223], v[196:199], v[16:19]
	v_mfma_f32_16x16x32_bf16 v[4:7], v[212:215], v[204:207], v[4:7]
	v_mfma_f32_16x16x32_bf16 v[0:3], v[220:223], v[204:207], v[0:3]
	s_setprio 0
	s_add_i32 s61, s61, 2
	s_add_u32 s38, s38, 0x100
	s_addc_u32 s39, s39, 0
	s_add_u32 s59, s59, 0x100
	s_addc_u32 s60, s60, 0
	s_cmp_gt_u32 s61, 29
	s_barrier
	s_cbranch_scc0 .LBB0_1346
	s_lshl_b32 s15, s36, 8
	s_add_i32 s15, s15, s51
	v_or_b32_e32 v154, s15, v145
	s_add_i32 s17, s15, 0xffffe000
	v_lshl_or_b32 v150, s33, 8, v157
	s_lshr_b32 s17, s17, 12
	v_lshlrev_b32_e32 v148, 12, v154
	s_add_i32 s17, s17, 1
	s_cmp_gt_i32 s15, s56
	s_cselect_b32 s17, s17, 0
	s_mul_i32 s17, s17, s54
	v_lshl_add_u32 v148, v150, 1, v148
	s_add_u32 s20, s8, s17
	s_addc_u32 s21, s9, 0
	v_lshlrev_b32_e32 v149, 2, v150
	s_nop 0
	global_load_dwordx4 v[196:199], v149, s[20:21]
	global_load_dwordx4 v[200:203], v149, s[20:21] offset:16
	global_load_dwordx4 v[204:207], v149, s[20:21] offset:512
	global_load_dwordx4 v[208:211], v149, s[20:21] offset:528
	global_load_dwordx4 v[212:215], v148, s[74:75]
	global_load_dwordx4 v[216:219], v148, s[74:75] offset:256
	v_add_u32_e32 v151, 0x10000, v148
	global_load_dwordx4 v[220:223], v151, s[74:75]
	global_load_dwordx4 v[224:227], v151, s[74:75] offset:256
	v_add_u32_e32 v151, 0x20000, v148
	global_load_dwordx4 v[164:167], v151, s[74:75]
	global_load_dwordx4 v[168:171], v151, s[74:75] offset:256
	v_add_u32_e32 v151, 0x30000, v148
	global_load_dwordx4 v[172:175], v151, s[74:75]
	global_load_dwordx4 v[176:179], v151, s[74:75] offset:256
	s_mov_b32 s33, s14
	s_mov_b32 s36, s16
	s_mov_b64 s[44:45], s[24:25]
	s_mov_b64 s[38:39], s[18:19]
	s_waitcnt vmcnt(0)
	v_lshlrev_b32_e32 v180, 16, v212
	v_and_b32_e32 v181, 0xffff0000, v212
	v_lshlrev_b32_e32 v182, 16, v213
	v_and_b32_e32 v183, 0xffff0000, v213
	v_lshlrev_b32_e32 v184, 16, v214
	v_and_b32_e32 v185, 0xffff0000, v214
	v_lshlrev_b32_e32 v186, 16, v215
	v_and_b32_e32 v187, 0xffff0000, v215
	v_pk_fma_f32 v[124:125], v[124:125], v[196:197], v[180:181]
	v_pk_fma_f32 v[126:127], v[126:127], v[198:199], v[182:183]
	v_pk_fma_f32 v[120:121], v[120:121], v[200:201], v[184:185]
	v_pk_fma_f32 v[122:123], v[122:123], v[202:203], v[186:187]
	v_cvt_pk_bf16_f32 v123, v122, v123
	v_cvt_pk_bf16_f32 v122, v120, v121
	v_cvt_pk_bf16_f32 v121, v126, v127
	v_cvt_pk_bf16_f32 v120, v124, v125
	global_store_dwordx4 v148, v[120:123], s[74:75]
	v_lshlrev_b32_e32 v180, 16, v216
	v_and_b32_e32 v181, 0xffff0000, v216
	v_lshlrev_b32_e32 v182, 16, v217
	v_and_b32_e32 v183, 0xffff0000, v217
	v_lshlrev_b32_e32 v184, 16, v218
	v_and_b32_e32 v185, 0xffff0000, v218
	v_lshlrev_b32_e32 v186, 16, v219
	v_and_b32_e32 v187, 0xffff0000, v219
	v_pk_fma_f32 v[116:117], v[116:117], v[204:205], v[180:181]
	v_pk_fma_f32 v[118:119], v[118:119], v[206:207], v[182:183]
	v_pk_fma_f32 v[112:113], v[112:113], v[208:209], v[184:185]
	v_pk_fma_f32 v[114:115], v[114:115], v[210:211], v[186:187]
	v_cvt_pk_bf16_f32 v115, v114, v115
	v_cvt_pk_bf16_f32 v114, v112, v113
	v_cvt_pk_bf16_f32 v113, v118, v119
	v_cvt_pk_bf16_f32 v112, v116, v117
	global_store_dwordx4 v148, v[112:115], s[74:75] offset:256
	v_lshlrev_b32_e32 v180, 16, v220
	v_and_b32_e32 v181, 0xffff0000, v220
	v_lshlrev_b32_e32 v182, 16, v221
	v_and_b32_e32 v183, 0xffff0000, v221
	v_lshlrev_b32_e32 v184, 16, v222
	v_and_b32_e32 v185, 0xffff0000, v222
	v_lshlrev_b32_e32 v186, 16, v223
	v_and_b32_e32 v187, 0xffff0000, v223
	v_pk_fma_f32 v[108:109], v[108:109], v[196:197], v[180:181]
	v_pk_fma_f32 v[110:111], v[110:111], v[198:199], v[182:183]
	v_pk_fma_f32 v[104:105], v[104:105], v[200:201], v[184:185]
	v_pk_fma_f32 v[106:107], v[106:107], v[202:203], v[186:187]
	v_cvt_pk_bf16_f32 v107, v106, v107
	v_cvt_pk_bf16_f32 v106, v104, v105
	v_cvt_pk_bf16_f32 v105, v110, v111
	v_cvt_pk_bf16_f32 v104, v108, v109
	v_add_u32_e32 v151, 0x10000, v148
	global_store_dwordx4 v151, v[104:107], s[74:75]
	v_lshlrev_b32_e32 v180, 16, v224
	v_and_b32_e32 v181, 0xffff0000, v224
	v_lshlrev_b32_e32 v182, 16, v225
	v_and_b32_e32 v183, 0xffff0000, v225
	v_lshlrev_b32_e32 v184, 16, v226
	v_and_b32_e32 v185, 0xffff0000, v226
	v_lshlrev_b32_e32 v186, 16, v227
	v_and_b32_e32 v187, 0xffff0000, v227
	v_pk_fma_f32 v[100:101], v[100:101], v[204:205], v[180:181]
	v_pk_fma_f32 v[102:103], v[102:103], v[206:207], v[182:183]
	v_pk_fma_f32 v[96:97], v[96:97], v[208:209], v[184:185]
	v_pk_fma_f32 v[98:99], v[98:99], v[210:211], v[186:187]
	v_cvt_pk_bf16_f32 v99, v98, v99
	v_cvt_pk_bf16_f32 v98, v96, v97
	v_cvt_pk_bf16_f32 v97, v102, v103
	v_cvt_pk_bf16_f32 v96, v100, v101
	v_add_u32_e32 v151, 0x10000, v148
	global_store_dwordx4 v151, v[96:99], s[74:75] offset:256
	v_add_u32_e32 v151, 0x80000, v148
	global_load_dwordx4 v[212:215], v151, s[74:75]
	global_load_dwordx4 v[216:219], v151, s[74:75] offset:256
	v_add_u32_e32 v151, 0x90000, v148
	global_load_dwordx4 v[220:223], v151, s[74:75]
	global_load_dwordx4 v[224:227], v151, s[74:75] offset:256
	v_lshlrev_b32_e32 v180, 16, v164
	v_and_b32_e32 v181, 0xffff0000, v164
	v_lshlrev_b32_e32 v182, 16, v165
	v_and_b32_e32 v183, 0xffff0000, v165
	v_lshlrev_b32_e32 v184, 16, v166
	v_and_b32_e32 v185, 0xffff0000, v166
	v_lshlrev_b32_e32 v186, 16, v167
	v_and_b32_e32 v187, 0xffff0000, v167
	v_pk_fma_f32 v[92:93], v[92:93], v[196:197], v[180:181]
	v_pk_fma_f32 v[94:95], v[94:95], v[198:199], v[182:183]
	v_pk_fma_f32 v[88:89], v[88:89], v[200:201], v[184:185]
	v_pk_fma_f32 v[90:91], v[90:91], v[202:203], v[186:187]
	v_cvt_pk_bf16_f32 v91, v90, v91
	v_cvt_pk_bf16_f32 v90, v88, v89
	v_cvt_pk_bf16_f32 v89, v94, v95
	v_cvt_pk_bf16_f32 v88, v92, v93
	v_add_u32_e32 v151, 0x20000, v148
	global_store_dwordx4 v151, v[88:91], s[74:75]
	v_lshlrev_b32_e32 v180, 16, v168
	v_and_b32_e32 v181, 0xffff0000, v168
	v_lshlrev_b32_e32 v182, 16, v169
	v_and_b32_e32 v183, 0xffff0000, v169
	v_lshlrev_b32_e32 v184, 16, v170
	v_and_b32_e32 v185, 0xffff0000, v170
	v_lshlrev_b32_e32 v186, 16, v171
	v_and_b32_e32 v187, 0xffff0000, v171
	v_pk_fma_f32 v[84:85], v[84:85], v[204:205], v[180:181]
	v_pk_fma_f32 v[86:87], v[86:87], v[206:207], v[182:183]
	v_pk_fma_f32 v[80:81], v[80:81], v[208:209], v[184:185]
	v_pk_fma_f32 v[82:83], v[82:83], v[210:211], v[186:187]
	v_cvt_pk_bf16_f32 v83, v82, v83
	v_cvt_pk_bf16_f32 v82, v80, v81
	v_cvt_pk_bf16_f32 v81, v86, v87
	v_cvt_pk_bf16_f32 v80, v84, v85
	v_add_u32_e32 v151, 0x20000, v148
	global_store_dwordx4 v151, v[80:83], s[74:75] offset:256
	v_lshlrev_b32_e32 v180, 16, v172
	v_and_b32_e32 v181, 0xffff0000, v172
	v_lshlrev_b32_e32 v182, 16, v173
	v_and_b32_e32 v183, 0xffff0000, v173
	v_lshlrev_b32_e32 v184, 16, v174
	v_and_b32_e32 v185, 0xffff0000, v174
	v_lshlrev_b32_e32 v186, 16, v175
	v_and_b32_e32 v187, 0xffff0000, v175
	v_pk_fma_f32 v[76:77], v[76:77], v[196:197], v[180:181]
	v_pk_fma_f32 v[78:79], v[78:79], v[198:199], v[182:183]
	v_pk_fma_f32 v[72:73], v[72:73], v[200:201], v[184:185]
	v_pk_fma_f32 v[74:75], v[74:75], v[202:203], v[186:187]
	v_cvt_pk_bf16_f32 v75, v74, v75
	v_cvt_pk_bf16_f32 v74, v72, v73
	v_cvt_pk_bf16_f32 v73, v78, v79
	v_cvt_pk_bf16_f32 v72, v76, v77
	v_add_u32_e32 v151, 0x30000, v148
	global_store_dwordx4 v151, v[72:75], s[74:75]
	v_lshlrev_b32_e32 v180, 16, v176
	v_and_b32_e32 v181, 0xffff0000, v176
	v_lshlrev_b32_e32 v182, 16, v177
	v_and_b32_e32 v183, 0xffff0000, v177
	v_lshlrev_b32_e32 v184, 16, v178
	v_and_b32_e32 v185, 0xffff0000, v178
	v_lshlrev_b32_e32 v186, 16, v179
	v_and_b32_e32 v187, 0xffff0000, v179
	v_pk_fma_f32 v[68:69], v[68:69], v[204:205], v[180:181]
	v_pk_fma_f32 v[70:71], v[70:71], v[206:207], v[182:183]
	v_pk_fma_f32 v[64:65], v[64:65], v[208:209], v[184:185]
	v_pk_fma_f32 v[66:67], v[66:67], v[210:211], v[186:187]
	v_cvt_pk_bf16_f32 v67, v66, v67
	v_cvt_pk_bf16_f32 v66, v64, v65
	v_cvt_pk_bf16_f32 v65, v70, v71
	v_cvt_pk_bf16_f32 v64, v68, v69
	v_add_u32_e32 v151, 0x30000, v148
	global_store_dwordx4 v151, v[64:67], s[74:75] offset:256
	v_add_u32_e32 v151, 0xa0000, v148
	global_load_dwordx4 v[164:167], v151, s[74:75]
	global_load_dwordx4 v[168:171], v151, s[74:75] offset:256
	v_add_u32_e32 v151, 0xb0000, v148
	global_load_dwordx4 v[172:175], v151, s[74:75]
	global_load_dwordx4 v[176:179], v151, s[74:75] offset:256
	s_waitcnt vmcnt(0)
	v_lshlrev_b32_e32 v180, 16, v212
	v_and_b32_e32 v181, 0xffff0000, v212
	v_lshlrev_b32_e32 v182, 16, v213
	v_and_b32_e32 v183, 0xffff0000, v213
	v_lshlrev_b32_e32 v184, 16, v214
	v_and_b32_e32 v185, 0xffff0000, v214
	v_lshlrev_b32_e32 v186, 16, v215
	v_and_b32_e32 v187, 0xffff0000, v215
	v_pk_fma_f32 v[60:61], v[60:61], v[196:197], v[180:181]
	v_pk_fma_f32 v[62:63], v[62:63], v[198:199], v[182:183]
	v_pk_fma_f32 v[56:57], v[56:57], v[200:201], v[184:185]
	v_pk_fma_f32 v[58:59], v[58:59], v[202:203], v[186:187]
	v_cvt_pk_bf16_f32 v59, v58, v59
	v_cvt_pk_bf16_f32 v58, v56, v57
	v_cvt_pk_bf16_f32 v57, v62, v63
	v_cvt_pk_bf16_f32 v56, v60, v61
	v_add_u32_e32 v151, 0x80000, v148
	global_store_dwordx4 v151, v[56:59], s[74:75]
	v_lshlrev_b32_e32 v180, 16, v216
	v_and_b32_e32 v181, 0xffff0000, v216
	v_lshlrev_b32_e32 v182, 16, v217
	v_and_b32_e32 v183, 0xffff0000, v217
	v_lshlrev_b32_e32 v184, 16, v218
	v_and_b32_e32 v185, 0xffff0000, v218
	v_lshlrev_b32_e32 v186, 16, v219
	v_and_b32_e32 v187, 0xffff0000, v219
	v_pk_fma_f32 v[52:53], v[52:53], v[204:205], v[180:181]
	v_pk_fma_f32 v[54:55], v[54:55], v[206:207], v[182:183]
	v_pk_fma_f32 v[48:49], v[48:49], v[208:209], v[184:185]
	v_pk_fma_f32 v[50:51], v[50:51], v[210:211], v[186:187]
	v_cvt_pk_bf16_f32 v51, v50, v51
	v_cvt_pk_bf16_f32 v50, v48, v49
	v_cvt_pk_bf16_f32 v49, v54, v55
	v_cvt_pk_bf16_f32 v48, v52, v53
	v_add_u32_e32 v151, 0x80000, v148
	global_store_dwordx4 v151, v[48:51], s[74:75] offset:256
	v_lshlrev_b32_e32 v180, 16, v220
	v_and_b32_e32 v181, 0xffff0000, v220
	v_lshlrev_b32_e32 v182, 16, v221
	v_and_b32_e32 v183, 0xffff0000, v221
	v_lshlrev_b32_e32 v184, 16, v222
	v_and_b32_e32 v185, 0xffff0000, v222
	v_lshlrev_b32_e32 v186, 16, v223
	v_and_b32_e32 v187, 0xffff0000, v223
	v_pk_fma_f32 v[44:45], v[44:45], v[196:197], v[180:181]
	v_pk_fma_f32 v[46:47], v[46:47], v[198:199], v[182:183]
	v_pk_fma_f32 v[40:41], v[40:41], v[200:201], v[184:185]
	v_pk_fma_f32 v[42:43], v[42:43], v[202:203], v[186:187]
	v_cvt_pk_bf16_f32 v43, v42, v43
	v_cvt_pk_bf16_f32 v42, v40, v41
	v_cvt_pk_bf16_f32 v41, v46, v47
	v_cvt_pk_bf16_f32 v40, v44, v45
	v_add_u32_e32 v151, 0x90000, v148
	global_store_dwordx4 v151, v[40:43], s[74:75]
	v_lshlrev_b32_e32 v180, 16, v224
	v_and_b32_e32 v181, 0xffff0000, v224
	v_lshlrev_b32_e32 v182, 16, v225
	v_and_b32_e32 v183, 0xffff0000, v225
	v_lshlrev_b32_e32 v184, 16, v226
	v_and_b32_e32 v185, 0xffff0000, v226
	v_lshlrev_b32_e32 v186, 16, v227
	v_and_b32_e32 v187, 0xffff0000, v227
	v_pk_fma_f32 v[36:37], v[36:37], v[204:205], v[180:181]
	v_pk_fma_f32 v[38:39], v[38:39], v[206:207], v[182:183]
	v_pk_fma_f32 v[32:33], v[32:33], v[208:209], v[184:185]
	v_pk_fma_f32 v[34:35], v[34:35], v[210:211], v[186:187]
	v_cvt_pk_bf16_f32 v35, v34, v35
	v_cvt_pk_bf16_f32 v34, v32, v33
	v_cvt_pk_bf16_f32 v33, v38, v39
	v_cvt_pk_bf16_f32 v32, v36, v37
	v_add_u32_e32 v151, 0x90000, v148
	global_store_dwordx4 v151, v[32:35], s[74:75] offset:256
	v_lshlrev_b32_e32 v180, 16, v164
	v_and_b32_e32 v181, 0xffff0000, v164
	v_lshlrev_b32_e32 v182, 16, v165
	v_and_b32_e32 v183, 0xffff0000, v165
	v_lshlrev_b32_e32 v184, 16, v166
	v_and_b32_e32 v185, 0xffff0000, v166
	v_lshlrev_b32_e32 v186, 16, v167
	v_and_b32_e32 v187, 0xffff0000, v167
	v_pk_fma_f32 v[28:29], v[28:29], v[196:197], v[180:181]
	v_pk_fma_f32 v[30:31], v[30:31], v[198:199], v[182:183]
	v_pk_fma_f32 v[24:25], v[24:25], v[200:201], v[184:185]
	v_pk_fma_f32 v[26:27], v[26:27], v[202:203], v[186:187]
	v_cvt_pk_bf16_f32 v27, v26, v27
	v_cvt_pk_bf16_f32 v26, v24, v25
	v_cvt_pk_bf16_f32 v25, v30, v31
	v_cvt_pk_bf16_f32 v24, v28, v29
	v_add_u32_e32 v151, 0xa0000, v148
	global_store_dwordx4 v151, v[24:27], s[74:75]
	v_lshlrev_b32_e32 v180, 16, v168
	v_and_b32_e32 v181, 0xffff0000, v168
	v_lshlrev_b32_e32 v182, 16, v169
	v_and_b32_e32 v183, 0xffff0000, v169
	v_lshlrev_b32_e32 v184, 16, v170
	v_and_b32_e32 v185, 0xffff0000, v170
	v_lshlrev_b32_e32 v186, 16, v171
	v_and_b32_e32 v187, 0xffff0000, v171
	v_pk_fma_f32 v[20:21], v[20:21], v[204:205], v[180:181]
	v_pk_fma_f32 v[22:23], v[22:23], v[206:207], v[182:183]
	v_pk_fma_f32 v[16:17], v[16:17], v[208:209], v[184:185]
	v_pk_fma_f32 v[18:19], v[18:19], v[210:211], v[186:187]
	v_cvt_pk_bf16_f32 v19, v18, v19
	v_cvt_pk_bf16_f32 v18, v16, v17
	v_cvt_pk_bf16_f32 v17, v22, v23
	v_cvt_pk_bf16_f32 v16, v20, v21
	v_add_u32_e32 v151, 0xa0000, v148
	global_store_dwordx4 v151, v[16:19], s[74:75] offset:256
	v_lshlrev_b32_e32 v180, 16, v172
	v_and_b32_e32 v181, 0xffff0000, v172
	v_lshlrev_b32_e32 v182, 16, v173
	v_and_b32_e32 v183, 0xffff0000, v173
	v_lshlrev_b32_e32 v184, 16, v174
	v_and_b32_e32 v185, 0xffff0000, v174
	v_lshlrev_b32_e32 v186, 16, v175
	v_and_b32_e32 v187, 0xffff0000, v175
	v_pk_fma_f32 v[12:13], v[12:13], v[196:197], v[180:181]
	v_pk_fma_f32 v[14:15], v[14:15], v[198:199], v[182:183]
	v_pk_fma_f32 v[8:9], v[8:9], v[200:201], v[184:185]
	v_pk_fma_f32 v[10:11], v[10:11], v[202:203], v[186:187]
	v_cvt_pk_bf16_f32 v11, v10, v11
	v_cvt_pk_bf16_f32 v10, v8, v9
	v_cvt_pk_bf16_f32 v9, v14, v15
	v_cvt_pk_bf16_f32 v8, v12, v13
	v_add_u32_e32 v151, 0xb0000, v148
	global_store_dwordx4 v151, v[8:11], s[74:75]
	v_lshlrev_b32_e32 v180, 16, v176
	v_and_b32_e32 v181, 0xffff0000, v176
	v_lshlrev_b32_e32 v182, 16, v177
	v_and_b32_e32 v183, 0xffff0000, v177
	v_lshlrev_b32_e32 v184, 16, v178
	v_and_b32_e32 v185, 0xffff0000, v178
	v_lshlrev_b32_e32 v186, 16, v179
	v_and_b32_e32 v187, 0xffff0000, v179
	v_pk_fma_f32 v[4:5], v[4:5], v[204:205], v[180:181]
	v_pk_fma_f32 v[6:7], v[6:7], v[206:207], v[182:183]
	v_pk_fma_f32 v[0:1], v[0:1], v[208:209], v[184:185]
	v_pk_fma_f32 v[2:3], v[2:3], v[210:211], v[186:187]
	v_cvt_pk_bf16_f32 v3, v2, v3
	v_cvt_pk_bf16_f32 v2, v0, v1
	v_cvt_pk_bf16_f32 v1, v6, v7
	v_cvt_pk_bf16_f32 v0, v4, v5
	v_add_u32_e32 v151, 0xb0000, v148
	global_store_dwordx4 v151, v[0:3], s[74:75] offset:256
	s_and_b64 vcc, exec, s[0:1]
	s_cbranch_vccz .LBB0_1343
	s_waitcnt vmcnt(0)
	s_cmpk_gt_u32 s12, 0xff
	s_cbranch_scc1 .LBB0_1350
	s_barrier

.LBB0_1433:
	ds_read_b128 v[148:151], v158
	ds_read_b128 v[152:155], v158 offset:1024
	ds_read_b128 v[162:165], v158 offset:2048
	ds_read_b128 v[166:169], v158 offset:3072
	s_add_u32 s20, s26, 0xffe00080
	s_addc_u32 s21, s27, -1
	s_cmpk_eq_i32 s53, 0x7c
	s_cselect_b32 s21, s15, s21
	s_cselect_b32 s20, s49, s20
	s_cselect_b32 s31, s11, s52
	s_cselect_b32 s30, s50, s51
	v_lshl_add_u64 v[204:205], s[26:27], 0, v[136:137]
	s_add_i32 m0, s25, 0xc000
	ds_read_b128 v[170:173], v159
	ds_read_b128 v[174:177], v159 offset:1024
	ds_read_b128 v[178:181], v159 offset:2048
	ds_read_b128 v[182:185], v159 offset:3072
	ds_read_b128 v[186:189], v159 offset:4096
	ds_read_b128 v[190:193], v159 offset:5120
	ds_read_b128 v[196:199], v159 offset:6144
	ds_read_b128 v[200:203], v159 offset:7168
	global_load_lds_dwordx4 v[204:205], off
	v_lshl_add_u64 v[204:205], s[26:27], 0, v[138:139]
	s_add_i32 m0, s25, 0xe000
	s_nop 0
	global_load_lds_dwordx4 v[204:205], off
	s_waitcnt lgkmcnt(8)
	s_barrier
	s_waitcnt lgkmcnt(0)
	s_setprio 1
	s_waitcnt lgkmcnt(0)
	v_mfma_f32_16x16x32_bf16 v[124:127], v[148:151], v[170:173], v[124:127]
	v_mfma_f32_16x16x32_bf16 v[120:123], v[162:165], v[170:173], v[120:123]
	v_mfma_f32_16x16x32_bf16 v[108:111], v[148:151], v[178:181], v[108:111]
	v_mfma_f32_16x16x32_bf16 v[104:107], v[162:165], v[178:181], v[104:107]
	v_mfma_f32_16x16x32_bf16 v[92:95], v[148:151], v[186:189], v[92:95]
	v_mfma_f32_16x16x32_bf16 v[88:91], v[162:165], v[186:189], v[88:91]
	v_mfma_f32_16x16x32_bf16 v[76:79], v[148:151], v[196:199], v[76:79]
	v_mfma_f32_16x16x32_bf16 v[72:75], v[162:165], v[196:199], v[72:75]
	v_mfma_f32_16x16x32_bf16 v[124:127], v[152:155], v[174:177], v[124:127]
	v_mfma_f32_16x16x32_bf16 v[120:123], v[166:169], v[174:177], v[120:123]
	v_mfma_f32_16x16x32_bf16 v[108:111], v[152:155], v[182:185], v[108:111]
	v_mfma_f32_16x16x32_bf16 v[104:107], v[166:169], v[182:185], v[104:107]
	v_mfma_f32_16x16x32_bf16 v[92:95], v[152:155], v[190:193], v[92:95]
	v_mfma_f32_16x16x32_bf16 v[88:91], v[166:169], v[190:193], v[88:91]
	v_mfma_f32_16x16x32_bf16 v[76:79], v[152:155], v[200:203], v[76:79]
	v_mfma_f32_16x16x32_bf16 v[72:75], v[166:169], v[200:203], v[72:75]
	s_setprio 0
	s_barrier
	s_add_i32 s54, s45, s23
	v_lshl_add_u64 v[220:221], s[30:31], 0, v[132:133]
	s_mov_b32 m0, s54
	ds_read_b128 v[204:207], v160
	ds_read_b128 v[208:211], v160 offset:1024
	ds_read_b128 v[212:215], v160 offset:2048
	ds_read_b128 v[216:219], v160 offset:3072
	global_load_lds_dwordx4 v[220:221], off
	v_lshl_add_u64 v[222:223], s[30:31], 0, v[128:129]
	s_add_i32 m0, s54, 0x2000
	s_nop 0
	global_load_lds_dwordx4 v[222:223], off
	s_barrier
	s_waitcnt lgkmcnt(0)
	s_setprio 1
	s_waitcnt lgkmcnt(0)
	v_mfma_f32_16x16x32_bf16 v[116:119], v[204:207], v[170:173], v[116:119]
	v_mfma_f32_16x16x32_bf16 v[112:115], v[212:215], v[170:173], v[112:115]
	v_mfma_f32_16x16x32_bf16 v[100:103], v[204:207], v[178:181], v[100:103]
	v_mfma_f32_16x16x32_bf16 v[96:99], v[212:215], v[178:181], v[96:99]
	v_mfma_f32_16x16x32_bf16 v[84:87], v[204:207], v[186:189], v[84:87]
	v_mfma_f32_16x16x32_bf16 v[80:83], v[212:215], v[186:189], v[80:83]
	v_mfma_f32_16x16x32_bf16 v[68:71], v[204:207], v[196:199], v[68:71]
	v_mfma_f32_16x16x32_bf16 v[64:67], v[212:215], v[196:199], v[64:67]
	v_mfma_f32_16x16x32_bf16 v[116:119], v[208:211], v[174:177], v[116:119]
	v_mfma_f32_16x16x32_bf16 v[112:115], v[216:219], v[174:177], v[112:115]
	v_mfma_f32_16x16x32_bf16 v[100:103], v[208:211], v[182:185], v[100:103]
	v_mfma_f32_16x16x32_bf16 v[96:99], v[216:219], v[182:185], v[96:99]
	v_mfma_f32_16x16x32_bf16 v[84:87], v[208:211], v[190:193], v[84:87]
	v_mfma_f32_16x16x32_bf16 v[80:83], v[216:219], v[190:193], v[80:83]
	v_mfma_f32_16x16x32_bf16 v[68:71], v[208:211], v[200:203], v[68:71]
	v_mfma_f32_16x16x32_bf16 v[64:67], v[216:219], v[200:203], v[64:67]
	s_setprio 0
	s_mov_b32 m0, s25
	v_lshl_add_u64 v[224:225], s[20:21], 0, v[134:135]
	s_barrier
	ds_read_b128 v[170:173], v159 offset:16384
	ds_read_b128 v[174:177], v159 offset:17408
	ds_read_b128 v[178:181], v159 offset:18432
	ds_read_b128 v[182:185], v159 offset:19456
	ds_read_b128 v[186:189], v159 offset:20480
	ds_read_b128 v[190:193], v159 offset:21504
	ds_read_b128 v[196:199], v159 offset:22528
	ds_read_b128 v[200:203], v159 offset:23552
	global_load_lds_dwordx4 v[224:225], off
	v_lshl_add_u64 v[226:227], s[20:21], 0, v[130:131]
	s_mov_b32 m0, s37
	s_nop 0
	global_load_lds_dwordx4 v[226:227], off
	s_barrier
	s_waitcnt lgkmcnt(0)
	s_setprio 1
	s_waitcnt lgkmcnt(0)
	v_mfma_f32_16x16x32_bf16 v[60:63], v[148:151], v[170:173], v[60:63]
	v_mfma_f32_16x16x32_bf16 v[56:59], v[162:165], v[170:173], v[56:59]
	v_mfma_f32_16x16x32_bf16 v[44:47], v[148:151], v[178:181], v[44:47]
	v_mfma_f32_16x16x32_bf16 v[40:43], v[162:165], v[178:181], v[40:43]
	v_mfma_f32_16x16x32_bf16 v[28:31], v[148:151], v[186:189], v[28:31]
	v_mfma_f32_16x16x32_bf16 v[24:27], v[162:165], v[186:189], v[24:27]
	v_mfma_f32_16x16x32_bf16 v[12:15], v[148:151], v[196:199], v[12:15]
	v_mfma_f32_16x16x32_bf16 v[8:11], v[162:165], v[196:199], v[8:11]
	v_mfma_f32_16x16x32_bf16 v[60:63], v[152:155], v[174:177], v[60:63]
	v_mfma_f32_16x16x32_bf16 v[56:59], v[166:169], v[174:177], v[56:59]
	v_mfma_f32_16x16x32_bf16 v[44:47], v[152:155], v[182:185], v[44:47]
	v_mfma_f32_16x16x32_bf16 v[40:43], v[166:169], v[182:185], v[40:43]
	v_mfma_f32_16x16x32_bf16 v[28:31], v[152:155], v[190:193], v[28:31]
	v_mfma_f32_16x16x32_bf16 v[24:27], v[166:169], v[190:193], v[24:27]
	v_mfma_f32_16x16x32_bf16 v[12:15], v[152:155], v[200:203], v[12:15]
	v_mfma_f32_16x16x32_bf16 v[8:11], v[166:169], v[200:203], v[8:11]
	s_setprio 0
	s_barrier
	s_add_u32 s54, s30, 0x200000
	s_addc_u32 s55, s31, 0
	s_add_i32 s56, s47, s23
	v_lshl_add_u64 v[148:149], s[54:55], 0, v[132:133]
	s_mov_b32 m0, s56
	s_nop 0
	global_load_lds_dwordx4 v[148:149], off
	v_lshl_add_u64 v[148:149], s[54:55], 0, v[128:129]
	s_add_i32 m0, s56, 0x2000
	s_nop 0
	global_load_lds_dwordx4 v[148:149], off
	s_waitcnt vmcnt(6)
	s_barrier
	s_setprio 1
	v_mfma_f32_16x16x32_bf16 v[52:55], v[204:207], v[170:173], v[52:55]
	v_mfma_f32_16x16x32_bf16 v[48:51], v[212:215], v[170:173], v[48:51]
	v_mfma_f32_16x16x32_bf16 v[36:39], v[204:207], v[178:181], v[36:39]
	v_mfma_f32_16x16x32_bf16 v[32:35], v[212:215], v[178:181], v[32:35]
	v_mfma_f32_16x16x32_bf16 v[20:23], v[204:207], v[186:189], v[20:23]
	v_mfma_f32_16x16x32_bf16 v[16:19], v[212:215], v[186:189], v[16:19]
	v_mfma_f32_16x16x32_bf16 v[4:7], v[204:207], v[196:199], v[4:7]
	v_mfma_f32_16x16x32_bf16 v[0:3], v[212:215], v[196:199], v[0:3]
	v_mfma_f32_16x16x32_bf16 v[52:55], v[208:211], v[174:177], v[52:55]
	v_mfma_f32_16x16x32_bf16 v[48:51], v[216:219], v[174:177], v[48:51]
	v_mfma_f32_16x16x32_bf16 v[36:39], v[208:211], v[182:185], v[36:39]
	v_mfma_f32_16x16x32_bf16 v[32:35], v[216:219], v[182:185], v[32:35]
	v_mfma_f32_16x16x32_bf16 v[20:23], v[208:211], v[190:193], v[20:23]
	v_mfma_f32_16x16x32_bf16 v[16:19], v[216:219], v[190:193], v[16:19]
	v_mfma_f32_16x16x32_bf16 v[4:7], v[208:211], v[200:203], v[4:7]
	v_mfma_f32_16x16x32_bf16 v[0:3], v[216:219], v[200:203], v[0:3]
	s_setprio 0
	s_add_i32 s54, 0, 0x18000
	v_add_u32_e32 v161, s54, v147
	s_barrier
	ds_read_b128 v[148:151], v161
	ds_read_b128 v[152:155], v161 offset:1024
	ds_read_b128 v[162:165], v161 offset:2048
	ds_read_b128 v[166:169], v161 offset:3072
	s_add_u32 s20, s20, 0x200000
	s_addc_u32 s21, s21, 0
	s_mov_b32 m0, s38
	v_lshl_add_u64 v[204:205], s[20:21], 0, v[134:135]
	ds_read_b128 v[170:173], v159 offset:32768
	ds_read_b128 v[174:177], v159 offset:33792
	ds_read_b128 v[178:181], v159 offset:34816
	ds_read_b128 v[182:185], v159 offset:35840
	ds_read_b128 v[186:189], v159 offset:36864
	ds_read_b128 v[190:193], v159 offset:37888
	ds_read_b128 v[196:199], v159 offset:38912
	ds_read_b128 v[200:203], v159 offset:39936
	global_load_lds_dwordx4 v[204:205], off
	v_lshl_add_u64 v[204:205], s[20:21], 0, v[130:131]
	s_mov_b32 m0, s39
	s_nop 0
	global_load_lds_dwordx4 v[204:205], off
	s_waitcnt lgkmcnt(8)
	s_barrier
	s_waitcnt lgkmcnt(0)
	s_setprio 1
	s_waitcnt lgkmcnt(0)
	v_mfma_f32_16x16x32_bf16 v[124:127], v[148:151], v[170:173], v[124:127]
	v_mfma_f32_16x16x32_bf16 v[120:123], v[162:165], v[170:173], v[120:123]
	v_mfma_f32_16x16x32_bf16 v[108:111], v[148:151], v[178:181], v[108:111]
	v_mfma_f32_16x16x32_bf16 v[104:107], v[162:165], v[178:181], v[104:107]
	v_mfma_f32_16x16x32_bf16 v[92:95], v[148:151], v[186:189], v[92:95]
	v_mfma_f32_16x16x32_bf16 v[88:91], v[162:165], v[186:189], v[88:91]
	v_mfma_f32_16x16x32_bf16 v[76:79], v[148:151], v[196:199], v[76:79]
	v_mfma_f32_16x16x32_bf16 v[72:75], v[162:165], v[196:199], v[72:75]
	v_mfma_f32_16x16x32_bf16 v[124:127], v[152:155], v[174:177], v[124:127]
	v_mfma_f32_16x16x32_bf16 v[120:123], v[166:169], v[174:177], v[120:123]
	v_mfma_f32_16x16x32_bf16 v[108:111], v[152:155], v[182:185], v[108:111]
	v_mfma_f32_16x16x32_bf16 v[104:107], v[166:169], v[182:185], v[104:107]
	v_mfma_f32_16x16x32_bf16 v[92:95], v[152:155], v[190:193], v[92:95]
	v_mfma_f32_16x16x32_bf16 v[88:91], v[166:169], v[190:193], v[88:91]
	v_mfma_f32_16x16x32_bf16 v[76:79], v[152:155], v[200:203], v[76:79]
	v_mfma_f32_16x16x32_bf16 v[72:75], v[166:169], v[200:203], v[72:75]
	s_setprio 0
	s_barrier
	s_add_i32 s55, 0, 0x1c000
	s_add_i32 s20, s54, s23
	v_add_u32_e32 v161, s55, v147
	v_lshl_add_u64 v[220:221], v[220:221], 0, s[8:9]
	s_mov_b32 m0, s20
	ds_read_b128 v[204:207], v161
	ds_read_b128 v[208:211], v161 offset:1024
	ds_read_b128 v[212:215], v161 offset:2048
	ds_read_b128 v[216:219], v161 offset:3072
	global_load_lds_dwordx4 v[220:221], off
	v_lshl_add_u64 v[220:221], v[222:223], 0, s[8:9]
	s_add_i32 m0, s20, 0x2000
	s_nop 0
	global_load_lds_dwordx4 v[220:221], off
	s_barrier
	s_waitcnt lgkmcnt(0)
	s_setprio 1
	s_waitcnt lgkmcnt(0)
	v_mfma_f32_16x16x32_bf16 v[116:119], v[204:207], v[170:173], v[116:119]
	v_mfma_f32_16x16x32_bf16 v[112:115], v[212:215], v[170:173], v[112:115]
	v_mfma_f32_16x16x32_bf16 v[100:103], v[204:207], v[178:181], v[100:103]
	v_mfma_f32_16x16x32_bf16 v[96:99], v[212:215], v[178:181], v[96:99]
	v_mfma_f32_16x16x32_bf16 v[84:87], v[204:207], v[186:189], v[84:87]
	v_mfma_f32_16x16x32_bf16 v[80:83], v[212:215], v[186:189], v[80:83]
	v_mfma_f32_16x16x32_bf16 v[68:71], v[204:207], v[196:199], v[68:71]
	v_mfma_f32_16x16x32_bf16 v[64:67], v[212:215], v[196:199], v[64:67]
	v_mfma_f32_16x16x32_bf16 v[116:119], v[208:211], v[174:177], v[116:119]
	v_mfma_f32_16x16x32_bf16 v[112:115], v[216:219], v[174:177], v[112:115]
	v_mfma_f32_16x16x32_bf16 v[100:103], v[208:211], v[182:185], v[100:103]
	v_mfma_f32_16x16x32_bf16 v[96:99], v[216:219], v[182:185], v[96:99]
	v_mfma_f32_16x16x32_bf16 v[84:87], v[208:211], v[190:193], v[84:87]
	v_mfma_f32_16x16x32_bf16 v[80:83], v[216:219], v[190:193], v[80:83]
	v_mfma_f32_16x16x32_bf16 v[68:71], v[208:211], v[200:203], v[68:71]
	v_mfma_f32_16x16x32_bf16 v[64:67], v[216:219], v[200:203], v[64:67]
	s_setprio 0
	s_mov_b32 m0, s35
	v_lshl_add_u64 v[220:221], v[224:225], 0, s[8:9]
	s_barrier
	ds_read_b128 v[170:173], v159 offset:49152
	ds_read_b128 v[174:177], v159 offset:50176
	ds_read_b128 v[178:181], v159 offset:51200
	ds_read_b128 v[182:185], v159 offset:52224
	ds_read_b128 v[186:189], v159 offset:53248
	ds_read_b128 v[190:193], v159 offset:54272
	ds_read_b128 v[196:199], v159 offset:55296
	ds_read_b128 v[200:203], v159 offset:56320
	global_load_lds_dwordx4 v[220:221], off
	v_lshl_add_u64 v[220:221], v[226:227], 0, s[8:9]
	s_mov_b32 m0, s41
	s_nop 0
	global_load_lds_dwordx4 v[220:221], off
	s_barrier
	s_waitcnt lgkmcnt(0)
	s_setprio 1
	s_waitcnt lgkmcnt(0)
	v_mfma_f32_16x16x32_bf16 v[60:63], v[148:151], v[170:173], v[60:63]
	v_mfma_f32_16x16x32_bf16 v[56:59], v[162:165], v[170:173], v[56:59]
	v_mfma_f32_16x16x32_bf16 v[44:47], v[148:151], v[178:181], v[44:47]
	v_mfma_f32_16x16x32_bf16 v[40:43], v[162:165], v[178:181], v[40:43]
	v_mfma_f32_16x16x32_bf16 v[28:31], v[148:151], v[186:189], v[28:31]
	v_mfma_f32_16x16x32_bf16 v[24:27], v[162:165], v[186:189], v[24:27]
	v_mfma_f32_16x16x32_bf16 v[12:15], v[148:151], v[196:199], v[12:15]
	v_mfma_f32_16x16x32_bf16 v[8:11], v[162:165], v[196:199], v[8:11]
	v_mfma_f32_16x16x32_bf16 v[60:63], v[152:155], v[174:177], v[60:63]
	v_mfma_f32_16x16x32_bf16 v[56:59], v[166:169], v[174:177], v[56:59]
	v_mfma_f32_16x16x32_bf16 v[44:47], v[152:155], v[182:185], v[44:47]
	v_mfma_f32_16x16x32_bf16 v[40:43], v[166:169], v[182:185], v[40:43]
	v_mfma_f32_16x16x32_bf16 v[28:31], v[152:155], v[190:193], v[28:31]
	v_mfma_f32_16x16x32_bf16 v[24:27], v[166:169], v[190:193], v[24:27]
	v_mfma_f32_16x16x32_bf16 v[12:15], v[152:155], v[200:203], v[12:15]
	v_mfma_f32_16x16x32_bf16 v[8:11], v[166:169], v[200:203], v[8:11]
	s_setprio 0
	s_barrier
	s_add_u32 s20, s30, 0x200080
	s_addc_u32 s21, s31, 0
	s_add_i32 s30, s55, s23
	v_lshl_add_u64 v[148:149], s[20:21], 0, v[132:133]
	s_mov_b32 m0, s30
	s_nop 0
	global_load_lds_dwordx4 v[148:149], off
	v_lshl_add_u64 v[148:149], s[20:21], 0, v[128:129]
	s_add_i32 m0, s30, 0x2000
	s_nop 0
	global_load_lds_dwordx4 v[148:149], off
	s_waitcnt vmcnt(6)
	s_barrier
	s_setprio 1
	v_mfma_f32_16x16x32_bf16 v[52:55], v[204:207], v[170:173], v[52:55]
	v_mfma_f32_16x16x32_bf16 v[48:51], v[212:215], v[170:173], v[48:51]
	v_mfma_f32_16x16x32_bf16 v[36:39], v[204:207], v[178:181], v[36:39]
	v_mfma_f32_16x16x32_bf16 v[32:35], v[212:215], v[178:181], v[32:35]
	v_mfma_f32_16x16x32_bf16 v[20:23], v[204:207], v[186:189], v[20:23]
	v_mfma_f32_16x16x32_bf16 v[16:19], v[212:215], v[186:189], v[16:19]
	v_mfma_f32_16x16x32_bf16 v[4:7], v[204:207], v[196:199], v[4:7]
	v_mfma_f32_16x16x32_bf16 v[0:3], v[212:215], v[196:199], v[0:3]
	v_mfma_f32_16x16x32_bf16 v[52:55], v[208:211], v[174:177], v[52:55]
	v_mfma_f32_16x16x32_bf16 v[48:51], v[216:219], v[174:177], v[48:51]
	v_mfma_f32_16x16x32_bf16 v[36:39], v[208:211], v[182:185], v[36:39]
	v_mfma_f32_16x16x32_bf16 v[32:35], v[216:219], v[182:185], v[32:35]
	v_mfma_f32_16x16x32_bf16 v[20:23], v[208:211], v[190:193], v[20:23]
	v_mfma_f32_16x16x32_bf16 v[16:19], v[216:219], v[190:193], v[16:19]
	v_mfma_f32_16x16x32_bf16 v[4:7], v[208:211], v[200:203], v[4:7]
	v_mfma_f32_16x16x32_bf16 v[0:3], v[216:219], v[200:203], v[0:3]
	s_setprio 0
	s_add_i32 s53, s53, 2
	s_add_u32 s26, s26, 0x100
	s_addc_u32 s27, s27, 0
	s_add_u32 s51, s51, 0x100
	s_addc_u32 s52, s52, 0
	s_cmpk_gt_u32 s53, 0x7d
	s_barrier
	s_cbranch_scc0 .LBB0_1433
	s_lshl_b32 s11, s24, 8
	s_add_i32 s11, s11, s34
	v_or_b32_e32 v154, s11, v145
	s_add_i32 s15, s11, 0xffffe000
	v_lshl_or_b32 v150, s33, 8, v157
	s_lshr_b32 s15, s15, 12
	v_lshlrev_b32_e32 v148, 12, v154
	s_add_i32 s15, s15, 1
	s_cmp_gt_i32 s11, s48
	s_cselect_b32 s15, s15, 0
	s_mul_i32 s15, s15, s46
	v_lshl_add_u32 v148, v150, 1, v148
	s_add_u32 s20, s6, s15
	s_addc_u32 s21, s7, 0
	v_lshlrev_b32_e32 v149, 2, v150
	s_nop 0
	global_load_dwordx4 v[196:199], v149, s[20:21]
	global_load_dwordx4 v[200:203], v149, s[20:21] offset:16
	global_load_dwordx4 v[204:207], v149, s[20:21] offset:512
	global_load_dwordx4 v[208:211], v149, s[20:21] offset:528
	global_load_dwordx4 v[212:215], v148, s[74:75]
	global_load_dwordx4 v[216:219], v148, s[74:75] offset:256
	v_add_u32_e32 v151, 0x10000, v148
	global_load_dwordx4 v[220:223], v151, s[74:75]
	global_load_dwordx4 v[224:227], v151, s[74:75] offset:256
	v_add_u32_e32 v151, 0x20000, v148
	global_load_dwordx4 v[164:167], v151, s[74:75]
	global_load_dwordx4 v[168:171], v151, s[74:75] offset:256
	v_add_u32_e32 v151, 0x30000, v148
	global_load_dwordx4 v[172:175], v151, s[74:75]
	global_load_dwordx4 v[176:179], v151, s[74:75] offset:256
	s_mov_b32 s33, s10
	s_mov_b32 s24, s14
	s_mov_b64 s[30:31], s[18:19]
	s_mov_b64 s[26:27], s[16:17]
	s_waitcnt vmcnt(0)
	v_lshlrev_b32_e32 v180, 16, v212
	v_and_b32_e32 v181, 0xffff0000, v212
	v_lshlrev_b32_e32 v182, 16, v213
	v_and_b32_e32 v183, 0xffff0000, v213
	v_lshlrev_b32_e32 v184, 16, v214
	v_and_b32_e32 v185, 0xffff0000, v214
	v_lshlrev_b32_e32 v186, 16, v215
	v_and_b32_e32 v187, 0xffff0000, v215
	v_pk_fma_f32 v[124:125], v[124:125], v[196:197], v[180:181]
	v_pk_fma_f32 v[126:127], v[126:127], v[198:199], v[182:183]
	v_pk_fma_f32 v[120:121], v[120:121], v[200:201], v[184:185]
	v_pk_fma_f32 v[122:123], v[122:123], v[202:203], v[186:187]
	v_cvt_pk_bf16_f32 v123, v122, v123
	v_cvt_pk_bf16_f32 v122, v120, v121
	v_cvt_pk_bf16_f32 v121, v126, v127
	v_cvt_pk_bf16_f32 v120, v124, v125
	global_store_dwordx4 v148, v[120:123], s[42:43]
	v_lshlrev_b32_e32 v180, 16, v216
	v_and_b32_e32 v181, 0xffff0000, v216
	v_lshlrev_b32_e32 v182, 16, v217
	v_and_b32_e32 v183, 0xffff0000, v217
	v_lshlrev_b32_e32 v184, 16, v218
	v_and_b32_e32 v185, 0xffff0000, v218
	v_lshlrev_b32_e32 v186, 16, v219
	v_and_b32_e32 v187, 0xffff0000, v219
	v_pk_fma_f32 v[116:117], v[116:117], v[204:205], v[180:181]
	v_pk_fma_f32 v[118:119], v[118:119], v[206:207], v[182:183]
	v_pk_fma_f32 v[112:113], v[112:113], v[208:209], v[184:185]
	v_pk_fma_f32 v[114:115], v[114:115], v[210:211], v[186:187]
	v_cvt_pk_bf16_f32 v115, v114, v115
	v_cvt_pk_bf16_f32 v114, v112, v113
	v_cvt_pk_bf16_f32 v113, v118, v119
	v_cvt_pk_bf16_f32 v112, v116, v117
	global_store_dwordx4 v148, v[112:115], s[42:43] offset:256
	v_lshlrev_b32_e32 v180, 16, v220
	v_and_b32_e32 v181, 0xffff0000, v220
	v_lshlrev_b32_e32 v182, 16, v221
	v_and_b32_e32 v183, 0xffff0000, v221
	v_lshlrev_b32_e32 v184, 16, v222
	v_and_b32_e32 v185, 0xffff0000, v222
	v_lshlrev_b32_e32 v186, 16, v223
	v_and_b32_e32 v187, 0xffff0000, v223
	v_pk_fma_f32 v[108:109], v[108:109], v[196:197], v[180:181]
	v_pk_fma_f32 v[110:111], v[110:111], v[198:199], v[182:183]
	v_pk_fma_f32 v[104:105], v[104:105], v[200:201], v[184:185]
	v_pk_fma_f32 v[106:107], v[106:107], v[202:203], v[186:187]
	v_cvt_pk_bf16_f32 v107, v106, v107
	v_cvt_pk_bf16_f32 v106, v104, v105
	v_cvt_pk_bf16_f32 v105, v110, v111
	v_cvt_pk_bf16_f32 v104, v108, v109
	v_add_u32_e32 v151, 0x10000, v148
	global_store_dwordx4 v151, v[104:107], s[42:43]
	v_lshlrev_b32_e32 v180, 16, v224
	v_and_b32_e32 v181, 0xffff0000, v224
	v_lshlrev_b32_e32 v182, 16, v225
	v_and_b32_e32 v183, 0xffff0000, v225
	v_lshlrev_b32_e32 v184, 16, v226
	v_and_b32_e32 v185, 0xffff0000, v226
	v_lshlrev_b32_e32 v186, 16, v227
	v_and_b32_e32 v187, 0xffff0000, v227
	v_pk_fma_f32 v[100:101], v[100:101], v[204:205], v[180:181]
	v_pk_fma_f32 v[102:103], v[102:103], v[206:207], v[182:183]
	v_pk_fma_f32 v[96:97], v[96:97], v[208:209], v[184:185]
	v_pk_fma_f32 v[98:99], v[98:99], v[210:211], v[186:187]
	v_cvt_pk_bf16_f32 v99, v98, v99
	v_cvt_pk_bf16_f32 v98, v96, v97
	v_cvt_pk_bf16_f32 v97, v102, v103
	v_cvt_pk_bf16_f32 v96, v100, v101
	v_add_u32_e32 v151, 0x10000, v148
	global_store_dwordx4 v151, v[96:99], s[42:43] offset:256
	v_add_u32_e32 v151, 0x80000, v148
	global_load_dwordx4 v[212:215], v151, s[74:75]
	global_load_dwordx4 v[216:219], v151, s[74:75] offset:256
	v_add_u32_e32 v151, 0x90000, v148
	global_load_dwordx4 v[220:223], v151, s[74:75]
	global_load_dwordx4 v[224:227], v151, s[74:75] offset:256
	v_lshlrev_b32_e32 v180, 16, v164
	v_and_b32_e32 v181, 0xffff0000, v164
	v_lshlrev_b32_e32 v182, 16, v165
	v_and_b32_e32 v183, 0xffff0000, v165
	v_lshlrev_b32_e32 v184, 16, v166
	v_and_b32_e32 v185, 0xffff0000, v166
	v_lshlrev_b32_e32 v186, 16, v167
	v_and_b32_e32 v187, 0xffff0000, v167
	v_pk_fma_f32 v[92:93], v[92:93], v[196:197], v[180:181]
	v_pk_fma_f32 v[94:95], v[94:95], v[198:199], v[182:183]
	v_pk_fma_f32 v[88:89], v[88:89], v[200:201], v[184:185]
	v_pk_fma_f32 v[90:91], v[90:91], v[202:203], v[186:187]
	v_cvt_pk_bf16_f32 v91, v90, v91
	v_cvt_pk_bf16_f32 v90, v88, v89
	v_cvt_pk_bf16_f32 v89, v94, v95
	v_cvt_pk_bf16_f32 v88, v92, v93
	v_add_u32_e32 v151, 0x20000, v148
	global_store_dwordx4 v151, v[88:91], s[42:43]
	v_lshlrev_b32_e32 v180, 16, v168
	v_and_b32_e32 v181, 0xffff0000, v168
	v_lshlrev_b32_e32 v182, 16, v169
	v_and_b32_e32 v183, 0xffff0000, v169
	v_lshlrev_b32_e32 v184, 16, v170
	v_and_b32_e32 v185, 0xffff0000, v170
	v_lshlrev_b32_e32 v186, 16, v171
	v_and_b32_e32 v187, 0xffff0000, v171
	v_pk_fma_f32 v[84:85], v[84:85], v[204:205], v[180:181]
	v_pk_fma_f32 v[86:87], v[86:87], v[206:207], v[182:183]
	v_pk_fma_f32 v[80:81], v[80:81], v[208:209], v[184:185]
	v_pk_fma_f32 v[82:83], v[82:83], v[210:211], v[186:187]
	v_cvt_pk_bf16_f32 v83, v82, v83
	v_cvt_pk_bf16_f32 v82, v80, v81
	v_cvt_pk_bf16_f32 v81, v86, v87
	v_cvt_pk_bf16_f32 v80, v84, v85
	v_add_u32_e32 v151, 0x20000, v148
	global_store_dwordx4 v151, v[80:83], s[42:43] offset:256
	v_lshlrev_b32_e32 v180, 16, v172
	v_and_b32_e32 v181, 0xffff0000, v172
	v_lshlrev_b32_e32 v182, 16, v173
	v_and_b32_e32 v183, 0xffff0000, v173
	v_lshlrev_b32_e32 v184, 16, v174
	v_and_b32_e32 v185, 0xffff0000, v174
	v_lshlrev_b32_e32 v186, 16, v175
	v_and_b32_e32 v187, 0xffff0000, v175
	v_pk_fma_f32 v[76:77], v[76:77], v[196:197], v[180:181]
	v_pk_fma_f32 v[78:79], v[78:79], v[198:199], v[182:183]
	v_pk_fma_f32 v[72:73], v[72:73], v[200:201], v[184:185]
	v_pk_fma_f32 v[74:75], v[74:75], v[202:203], v[186:187]
	v_cvt_pk_bf16_f32 v75, v74, v75
	v_cvt_pk_bf16_f32 v74, v72, v73
	v_cvt_pk_bf16_f32 v73, v78, v79
	v_cvt_pk_bf16_f32 v72, v76, v77
	v_add_u32_e32 v151, 0x30000, v148
	global_store_dwordx4 v151, v[72:75], s[42:43]
	v_lshlrev_b32_e32 v180, 16, v176
	v_and_b32_e32 v181, 0xffff0000, v176
	v_lshlrev_b32_e32 v182, 16, v177
	v_and_b32_e32 v183, 0xffff0000, v177
	v_lshlrev_b32_e32 v184, 16, v178
	v_and_b32_e32 v185, 0xffff0000, v178
	v_lshlrev_b32_e32 v186, 16, v179
	v_and_b32_e32 v187, 0xffff0000, v179
	v_pk_fma_f32 v[68:69], v[68:69], v[204:205], v[180:181]
	v_pk_fma_f32 v[70:71], v[70:71], v[206:207], v[182:183]
	v_pk_fma_f32 v[64:65], v[64:65], v[208:209], v[184:185]
	v_pk_fma_f32 v[66:67], v[66:67], v[210:211], v[186:187]
	v_cvt_pk_bf16_f32 v67, v66, v67
	v_cvt_pk_bf16_f32 v66, v64, v65
	v_cvt_pk_bf16_f32 v65, v70, v71
	v_cvt_pk_bf16_f32 v64, v68, v69
	v_add_u32_e32 v151, 0x30000, v148
	global_store_dwordx4 v151, v[64:67], s[42:43] offset:256
	v_add_u32_e32 v151, 0xa0000, v148
	global_load_dwordx4 v[164:167], v151, s[74:75]
	global_load_dwordx4 v[168:171], v151, s[74:75] offset:256
	v_add_u32_e32 v151, 0xb0000, v148
	global_load_dwordx4 v[172:175], v151, s[74:75]
	global_load_dwordx4 v[176:179], v151, s[74:75] offset:256
	s_waitcnt vmcnt(0)
	v_lshlrev_b32_e32 v180, 16, v212
	v_and_b32_e32 v181, 0xffff0000, v212
	v_lshlrev_b32_e32 v182, 16, v213
	v_and_b32_e32 v183, 0xffff0000, v213
	v_lshlrev_b32_e32 v184, 16, v214
	v_and_b32_e32 v185, 0xffff0000, v214
	v_lshlrev_b32_e32 v186, 16, v215
	v_and_b32_e32 v187, 0xffff0000, v215
	v_pk_fma_f32 v[60:61], v[60:61], v[196:197], v[180:181]
	v_pk_fma_f32 v[62:63], v[62:63], v[198:199], v[182:183]
	v_pk_fma_f32 v[56:57], v[56:57], v[200:201], v[184:185]
	v_pk_fma_f32 v[58:59], v[58:59], v[202:203], v[186:187]
	v_cvt_pk_bf16_f32 v59, v58, v59
	v_cvt_pk_bf16_f32 v58, v56, v57
	v_cvt_pk_bf16_f32 v57, v62, v63
	v_cvt_pk_bf16_f32 v56, v60, v61
	v_add_u32_e32 v151, 0x80000, v148
	global_store_dwordx4 v151, v[56:59], s[42:43]
	v_lshlrev_b32_e32 v180, 16, v216
	v_and_b32_e32 v181, 0xffff0000, v216
	v_lshlrev_b32_e32 v182, 16, v217
	v_and_b32_e32 v183, 0xffff0000, v217
	v_lshlrev_b32_e32 v184, 16, v218
	v_and_b32_e32 v185, 0xffff0000, v218
	v_lshlrev_b32_e32 v186, 16, v219
	v_and_b32_e32 v187, 0xffff0000, v219
	v_pk_fma_f32 v[52:53], v[52:53], v[204:205], v[180:181]
	v_pk_fma_f32 v[54:55], v[54:55], v[206:207], v[182:183]
	v_pk_fma_f32 v[48:49], v[48:49], v[208:209], v[184:185]
	v_pk_fma_f32 v[50:51], v[50:51], v[210:211], v[186:187]
	v_cvt_pk_bf16_f32 v51, v50, v51
	v_cvt_pk_bf16_f32 v50, v48, v49
	v_cvt_pk_bf16_f32 v49, v54, v55
	v_cvt_pk_bf16_f32 v48, v52, v53
	v_add_u32_e32 v151, 0x80000, v148
	global_store_dwordx4 v151, v[48:51], s[42:43] offset:256
	v_lshlrev_b32_e32 v180, 16, v220
	v_and_b32_e32 v181, 0xffff0000, v220
	v_lshlrev_b32_e32 v182, 16, v221
	v_and_b32_e32 v183, 0xffff0000, v221
	v_lshlrev_b32_e32 v184, 16, v222
	v_and_b32_e32 v185, 0xffff0000, v222
	v_lshlrev_b32_e32 v186, 16, v223
	v_and_b32_e32 v187, 0xffff0000, v223
	v_pk_fma_f32 v[44:45], v[44:45], v[196:197], v[180:181]
	v_pk_fma_f32 v[46:47], v[46:47], v[198:199], v[182:183]
	v_pk_fma_f32 v[40:41], v[40:41], v[200:201], v[184:185]
	v_pk_fma_f32 v[42:43], v[42:43], v[202:203], v[186:187]
	v_cvt_pk_bf16_f32 v43, v42, v43
	v_cvt_pk_bf16_f32 v42, v40, v41
	v_cvt_pk_bf16_f32 v41, v46, v47
	v_cvt_pk_bf16_f32 v40, v44, v45
	v_add_u32_e32 v151, 0x90000, v148
	global_store_dwordx4 v151, v[40:43], s[42:43]
	v_lshlrev_b32_e32 v180, 16, v224
	v_and_b32_e32 v181, 0xffff0000, v224
	v_lshlrev_b32_e32 v182, 16, v225
	v_and_b32_e32 v183, 0xffff0000, v225
	v_lshlrev_b32_e32 v184, 16, v226
	v_and_b32_e32 v185, 0xffff0000, v226
	v_lshlrev_b32_e32 v186, 16, v227
	v_and_b32_e32 v187, 0xffff0000, v227
	v_pk_fma_f32 v[36:37], v[36:37], v[204:205], v[180:181]
	v_pk_fma_f32 v[38:39], v[38:39], v[206:207], v[182:183]
	v_pk_fma_f32 v[32:33], v[32:33], v[208:209], v[184:185]
	v_pk_fma_f32 v[34:35], v[34:35], v[210:211], v[186:187]
	v_cvt_pk_bf16_f32 v35, v34, v35
	v_cvt_pk_bf16_f32 v34, v32, v33
	v_cvt_pk_bf16_f32 v33, v38, v39
	v_cvt_pk_bf16_f32 v32, v36, v37
	v_add_u32_e32 v151, 0x90000, v148
	global_store_dwordx4 v151, v[32:35], s[42:43] offset:256
	v_lshlrev_b32_e32 v180, 16, v164
	v_and_b32_e32 v181, 0xffff0000, v164
	v_lshlrev_b32_e32 v182, 16, v165
	v_and_b32_e32 v183, 0xffff0000, v165
	v_lshlrev_b32_e32 v184, 16, v166
	v_and_b32_e32 v185, 0xffff0000, v166
	v_lshlrev_b32_e32 v186, 16, v167
	v_and_b32_e32 v187, 0xffff0000, v167
	v_pk_fma_f32 v[28:29], v[28:29], v[196:197], v[180:181]
	v_pk_fma_f32 v[30:31], v[30:31], v[198:199], v[182:183]
	v_pk_fma_f32 v[24:25], v[24:25], v[200:201], v[184:185]
	v_pk_fma_f32 v[26:27], v[26:27], v[202:203], v[186:187]
	v_cvt_pk_bf16_f32 v27, v26, v27
	v_cvt_pk_bf16_f32 v26, v24, v25
	v_cvt_pk_bf16_f32 v25, v30, v31
	v_cvt_pk_bf16_f32 v24, v28, v29
	v_add_u32_e32 v151, 0xa0000, v148
	global_store_dwordx4 v151, v[24:27], s[42:43]
	v_lshlrev_b32_e32 v180, 16, v168
	v_and_b32_e32 v181, 0xffff0000, v168
	v_lshlrev_b32_e32 v182, 16, v169
	v_and_b32_e32 v183, 0xffff0000, v169
	v_lshlrev_b32_e32 v184, 16, v170
	v_and_b32_e32 v185, 0xffff0000, v170
	v_lshlrev_b32_e32 v186, 16, v171
	v_and_b32_e32 v187, 0xffff0000, v171
	v_pk_fma_f32 v[20:21], v[20:21], v[204:205], v[180:181]
	v_pk_fma_f32 v[22:23], v[22:23], v[206:207], v[182:183]
	v_pk_fma_f32 v[16:17], v[16:17], v[208:209], v[184:185]
	v_pk_fma_f32 v[18:19], v[18:19], v[210:211], v[186:187]
	v_cvt_pk_bf16_f32 v19, v18, v19
	v_cvt_pk_bf16_f32 v18, v16, v17
	v_cvt_pk_bf16_f32 v17, v22, v23
	v_cvt_pk_bf16_f32 v16, v20, v21
	v_add_u32_e32 v151, 0xa0000, v148
	global_store_dwordx4 v151, v[16:19], s[42:43] offset:256
	v_lshlrev_b32_e32 v180, 16, v172
	v_and_b32_e32 v181, 0xffff0000, v172
	v_lshlrev_b32_e32 v182, 16, v173
	v_and_b32_e32 v183, 0xffff0000, v173
	v_lshlrev_b32_e32 v184, 16, v174
	v_and_b32_e32 v185, 0xffff0000, v174
	v_lshlrev_b32_e32 v186, 16, v175
	v_and_b32_e32 v187, 0xffff0000, v175
	v_pk_fma_f32 v[12:13], v[12:13], v[196:197], v[180:181]
	v_pk_fma_f32 v[14:15], v[14:15], v[198:199], v[182:183]
	v_pk_fma_f32 v[8:9], v[8:9], v[200:201], v[184:185]
	v_pk_fma_f32 v[10:11], v[10:11], v[202:203], v[186:187]
	v_cvt_pk_bf16_f32 v11, v10, v11
	v_cvt_pk_bf16_f32 v10, v8, v9
	v_cvt_pk_bf16_f32 v9, v14, v15
	v_cvt_pk_bf16_f32 v8, v12, v13
	v_add_u32_e32 v151, 0xb0000, v148
	global_store_dwordx4 v151, v[8:11], s[42:43]
	v_lshlrev_b32_e32 v180, 16, v176
	v_and_b32_e32 v181, 0xffff0000, v176
	v_lshlrev_b32_e32 v182, 16, v177
	v_and_b32_e32 v183, 0xffff0000, v177
	v_lshlrev_b32_e32 v184, 16, v178
	v_and_b32_e32 v185, 0xffff0000, v178
	v_lshlrev_b32_e32 v186, 16, v179
	v_and_b32_e32 v187, 0xffff0000, v179
	v_pk_fma_f32 v[4:5], v[4:5], v[204:205], v[180:181]
	v_pk_fma_f32 v[6:7], v[6:7], v[206:207], v[182:183]
	v_pk_fma_f32 v[0:1], v[0:1], v[208:209], v[184:185]
	v_pk_fma_f32 v[2:3], v[2:3], v[210:211], v[186:187]
	v_cvt_pk_bf16_f32 v3, v2, v3
	v_cvt_pk_bf16_f32 v2, v0, v1
	v_cvt_pk_bf16_f32 v1, v6, v7
	v_cvt_pk_bf16_f32 v0, v4, v5
	v_add_u32_e32 v151, 0xb0000, v148
	global_store_dwordx4 v151, v[0:3], s[42:43] offset:256
	s_and_b64 vcc, exec, s[0:1]
	s_cbranch_vccz .LBB0_1430
	s_waitcnt vmcnt(0)
	s_cmpk_gt_u32 s12, 0xff
	s_cbranch_scc1 .LBB0_1437
	s_barrier
